# P10 prompt rows (x2, XN) rewritten by hand with five rows of loads in flight per wave
# baseline (speedup 1.0000x reference)
; __device__ __forceinline__ float lo_bf(unsigned x) { return __uint_as_float(x << 16); }
; __device__ __forceinline__ float hi_bf(unsigned x) { return __uint_as_float(x & 0xffff0000u); }
; __device__ __forceinline__ void rows_proc(PR P, const int mode, const int row, const int lane, float4 (&xv)[4], const float4 (&fo)[4], const float4 (&gp)[4], const float4 (&gn)[4]) {
;     ...
;     if (mode != 0) {
;         float ss = 0.f;
; #pragma unroll
;         for (int q = 0; q < 4; ++q) ss += fo[q].x * fo[q].x + fo[q].y * fo[q].y + fo[q].z * fo[q].z + fo[q].w * fo[q].w;
;         ss = wave_sum(ss); const float r = rsqrtf(ss * (1.0f / 1024.0f) + 1e-6f) * (mode == 2 ? 1.0f : 0.5f);
; __device__ __forceinline__ void rows_phase(PR P, const int mode, LAS float* ldsf, const int wv) {
;     ...
;     const float* gpost = P.norm_g + (mode == 1 ? 1 : (mode == 2 ? 3 : 5)) * 1024;
;     const float* gnext = P.norm_g + (mode == 0 ? 0 : (mode == 1 ? 2 : 4)) * 1024;
;     float4 gp[4], gn[4];
; #pragma unroll
;     for (int q = 0; q < 4; ++q) { gp[q] = *(const float4*)(gpost + (q * 64 + lane) * 4); gn[q] = *(const float4*)(gnext + (q * 64 + lane) * 4); }
;     if (gw < MP) {
;         const int last = gw + ((MP - 1 - gw) / nw) * nw;
;         RowRaw R, N;
;         rows_load(P, mode, gw, lane, R);
;         for (int row = gw; row < MP; row += nw) {
;             const int nrow = row + nw < MP ? row + nw : last;
;             rows_load(P, mode, nrow, lane, N);
;             float4 xv[4], fo[4];
; #pragma unroll
;             for (int q = 0; q < 4; ++q) {
;                 xv[q] = mode <= 1 ? R.xf[q] : make_float4(lo_bf(R.xb[q].x), hi_bf(R.xb[q].x), lo_bf(R.xb[q].y), hi_bf(R.xb[q].y));
;                 fo[q] = make_float4(lo_bf(R.fb[q].x), hi_bf(R.fb[q].x), lo_bf(R.fb[q].y), hi_bf(R.fb[q].y)); }
.LBB0_928:
	v_mbcnt_lo_u32_b32 v0, -1, 0
	v_mbcnt_hi_u32_b32 v0, -1, v0
	s_load_dwordx2 s[0:1], s[38:39], 0x28
	v_add_u32_e32 v33, s33, v0
	v_and_b32_e32 v75, 63, v0
	v_ashrrev_i32_e32 v74, 6, v33
	v_lshlrev_b32_e32 v76, 2, v75
	s_waitcnt lgkmcnt(0)
	s_add_u32 s8, s0, 0x3000
	s_addc_u32 s9, s1, 0
	s_add_u32 s6, s0, 0x4000
	v_add_u32_e32 v34, s73, v74
	s_movk_i32 s16, 0x4000
	s_addc_u32 s7, s1, 0
	v_mov_b32_e32 v39, 0
	v_cmp_gt_i32_e32 vcc, s16, v34
	v_lshlrev_b32_e32 v32, 2, v76
	s_and_saveexec_b64 s[4:5], vcc
	s_cbranch_execz .LBB0_931
	global_load_dwordx4 v[0:3], v32, s[8:9]
	global_load_dwordx4 v[16:19], v32, s[6:7]
	global_load_dwordx4 v[4:7], v32, s[8:9] offset:1024
	global_load_dwordx4 v[20:23], v32, s[6:7] offset:1024
	global_load_dwordx4 v[8:11], v32, s[8:9] offset:2048
	global_load_dwordx4 v[24:27], v32, s[6:7] offset:2048
	global_load_dwordx4 v[12:15], v32, s[8:9] offset:3072
	global_load_dwordx4 v[28:31], v32, s[6:7] offset:3072
	s_load_dwordx2 s[0:1], s[38:39], 0xd0
	s_lshr_b32 s17, s33, 6
	s_add_i32 s17, s17, s73
	s_lshl_b32 s17, s17, 11
	v_lshl_add_u32 v36, v75, 3, s17
	v_mov_b32_e32 v214, 0x358637bd
	s_add_u32 s10, s12, 0x9804800
	s_addc_u32 s11, s13, 0
	s_add_u32 s14, s12, 0xb904800
	s_addc_u32 s15, s13, 0
	s_add_u32 s18, s12, 0x1bc4800
	s_addc_u32 s19, s13, 0
	s_waitcnt lgkmcnt(0)
	v_mov_b32_e32 v34, v36
	global_load_dwordx2 v[80:81], v34, s[0:1] offset:0 nt
	global_load_dwordx2 v[82:83], v34, s[0:1] offset:512 nt
	global_load_dwordx2 v[84:85], v34, s[0:1] offset:1024 nt
	global_load_dwordx2 v[86:87], v34, s[0:1] offset:1536 nt
	global_load_dwordx2 v[88:89], v34, s[10:11] offset:0 nt
	global_load_dwordx2 v[90:91], v34, s[10:11] offset:512 nt
	global_load_dwordx2 v[92:93], v34, s[10:11] offset:1024 nt
	global_load_dwordx2 v[94:95], v34, s[10:11] offset:1536 nt
	v_add_u32_e32 v34, 0x400000, v36
	global_load_dwordx2 v[96:97], v34, s[0:1] offset:0 nt
	global_load_dwordx2 v[98:99], v34, s[0:1] offset:512 nt
	global_load_dwordx2 v[100:101], v34, s[0:1] offset:1024 nt
	global_load_dwordx2 v[102:103], v34, s[0:1] offset:1536 nt
	global_load_dwordx2 v[104:105], v34, s[10:11] offset:0 nt
	global_load_dwordx2 v[106:107], v34, s[10:11] offset:512 nt
	global_load_dwordx2 v[108:109], v34, s[10:11] offset:1024 nt
	global_load_dwordx2 v[110:111], v34, s[10:11] offset:1536 nt
	v_add_u32_e32 v34, 0x800000, v36
	global_load_dwordx2 v[112:113], v34, s[0:1] offset:0 nt
	global_load_dwordx2 v[114:115], v34, s[0:1] offset:512 nt
	global_load_dwordx2 v[116:117], v34, s[0:1] offset:1024 nt
	global_load_dwordx2 v[118:119], v34, s[0:1] offset:1536 nt
	global_load_dwordx2 v[120:121], v34, s[10:11] offset:0 nt
	global_load_dwordx2 v[122:123], v34, s[10:11] offset:512 nt
	global_load_dwordx2 v[124:125], v34, s[10:11] offset:1024 nt
	global_load_dwordx2 v[126:127], v34, s[10:11] offset:1536 nt
	v_add_u32_e32 v34, 0xc00000, v36
	global_load_dwordx2 v[128:129], v34, s[0:1] offset:0 nt
	global_load_dwordx2 v[130:131], v34, s[0:1] offset:512 nt
	global_load_dwordx2 v[132:133], v34, s[0:1] offset:1024 nt
	global_load_dwordx2 v[134:135], v34, s[0:1] offset:1536 nt
	global_load_dwordx2 v[136:137], v34, s[10:11] offset:0 nt
	global_load_dwordx2 v[138:139], v34, s[10:11] offset:512 nt
	global_load_dwordx2 v[140:141], v34, s[10:11] offset:1024 nt
	global_load_dwordx2 v[142:143], v34, s[10:11] offset:1536 nt
	v_add_u32_e32 v34, 0x1000000, v36
	global_load_dwordx2 v[144:145], v34, s[0:1] offset:0 nt
	global_load_dwordx2 v[146:147], v34, s[0:1] offset:512 nt
	global_load_dwordx2 v[148:149], v34, s[0:1] offset:1024 nt
	global_load_dwordx2 v[150:151], v34, s[0:1] offset:1536 nt
	global_load_dwordx2 v[152:153], v34, s[10:11] offset:0 nt
	global_load_dwordx2 v[154:155], v34, s[10:11] offset:512 nt
	global_load_dwordx2 v[156:157], v34, s[10:11] offset:1024 nt
	global_load_dwordx2 v[158:159], v34, s[10:11] offset:1536 nt
	s_waitcnt vmcnt(32)
	v_lshlrev_b32_e32 v196, 16, v88
	v_and_b32_e32 v197, 0xffff0000, v88
	v_lshlrev_b32_e32 v198, 16, v89
	v_and_b32_e32 v199, 0xffff0000, v89
	v_lshlrev_b32_e32 v200, 16, v90
	v_and_b32_e32 v201, 0xffff0000, v90
	v_lshlrev_b32_e32 v202, 16, v91
	v_and_b32_e32 v203, 0xffff0000, v91
	v_lshlrev_b32_e32 v204, 16, v92
	v_and_b32_e32 v205, 0xffff0000, v92
	v_lshlrev_b32_e32 v206, 16, v93
	v_and_b32_e32 v207, 0xffff0000, v93
	v_lshlrev_b32_e32 v208, 16, v94
	v_and_b32_e32 v209, 0xffff0000, v94
	v_lshlrev_b32_e32 v210, 16, v95
	v_and_b32_e32 v211, 0xffff0000, v95
	v_pk_mul_f32 v[212:213], v[196:197], v[196:197]
	v_pk_fma_f32 v[212:213], v[198:199], v[198:199], v[212:213]
	v_pk_fma_f32 v[212:213], v[200:201], v[200:201], v[212:213]
	v_pk_fma_f32 v[212:213], v[202:203], v[202:203], v[212:213]
	v_pk_fma_f32 v[212:213], v[204:205], v[204:205], v[212:213]
	v_pk_fma_f32 v[212:213], v[206:207], v[206:207], v[212:213]
	v_pk_fma_f32 v[212:213], v[208:209], v[208:209], v[212:213]
	v_pk_fma_f32 v[212:213], v[210:211], v[210:211], v[212:213]
	v_add_f32_e32 v212, v212, v213
	v_lshlrev_b32_e32 v180, 16, v80
	v_and_b32_e32 v181, 0xffff0000, v80
	v_lshlrev_b32_e32 v182, 16, v81
	v_and_b32_e32 v183, 0xffff0000, v81
	v_add_f32_dpp v212, v212, v212 quad_perm:[1,0,3,2] row_mask:0xf bank_mask:0xf bound_ctrl:1
	v_lshlrev_b32_e32 v184, 16, v82
	v_and_b32_e32 v185, 0xffff0000, v82
	v_lshlrev_b32_e32 v186, 16, v83
	v_and_b32_e32 v187, 0xffff0000, v83
	v_add_f32_dpp v212, v212, v212 quad_perm:[2,3,0,1] row_mask:0xf bank_mask:0xf bound_ctrl:1
	v_lshlrev_b32_e32 v188, 16, v84
	v_and_b32_e32 v189, 0xffff0000, v84
	v_lshlrev_b32_e32 v190, 16, v85
	v_and_b32_e32 v191, 0xffff0000, v85
	v_add_f32_dpp v212, v212, v212 row_half_mirror row_mask:0xf bank_mask:0xf bound_ctrl:1
; __device__ __forceinline__ void rows_proc(PR P, const int mode, const int row, const int lane, float4 (&xv)[4], const float4 (&fo)[4], const float4 (&gp)[4], const float4 (&gn)[4]) {
;     ...
;     if (mode != 0) {
;         float ss = 0.f;
; #pragma unroll
;         for (int q = 0; q < 4; ++q) ss += fo[q].x * fo[q].x + fo[q].y * fo[q].y + fo[q].z * fo[q].z + fo[q].w * fo[q].w;
;         ss = wave_sum(ss); const float r = rsqrtf(ss * (1.0f / 1024.0f) + 1e-6f) * (mode == 2 ? 1.0f : 0.5f);
; #pragma unroll
;         for (int q = 0; q < 4; ++q) {
;             xv[q].x += fo[q].x * r * gp[q].x; xv[q].y += fo[q].y * r * gp[q].y; xv[q].z += fo[q].z * r * gp[q].z; xv[q].w += fo[q].w * r * gp[q].w;
;             if (mode == 3) { const f32x4 t_ = {xv[q].x, xv[q].y, xv[q].z, xv[q].w}; __builtin_nontemporal_store(t_, (f32x4*)(P.out + (size_t)row * 1024 + (q * 64 + lane) * 4)); }
;             else { bf16_t* xo = (mode == 1 ? (bf16_t*)P.out : (bf16_t*)(P.ws + WS_FO + 34603008)) + (size_t)row * 1024; u32x2 t; t.x = pg8::cvt_pk_bf16(xv[q].x, xv[q].y); t.y = pg8::cvt_pk_bf16(xv[q].z, xv[q].w);
;                 __builtin_nontemporal_store(t, (u32x2*)(xo + (q * 64 + lane) * 4)); } }
;         if (mode == 3) return;
;     }
;     float ss2 = 0.f;
; #pragma unroll
;     for (int q = 0; q < 4; ++q) ss2 += xv[q].x * xv[q].x + xv[q].y * xv[q].y + xv[q].z * xv[q].z + xv[q].w * xv[q].w;
;     ss2 = wave_sum(ss2); const float r2 = rsqrtf(ss2 * (1.0f / 1024.0f) + 1e-6f);
;     float* sh = nullptr;
;     if (mode == 1) { if (row < MP) { if ((row & 2047) == 2047) sh = P.out + O_SHP + (size_t)(row >> 11) * 1024; } else { const int s = row - MP; if ((s & 3) == 3) sh = P.out + O_SHS + (size_t)(s >> 2) * 1024; } }
; #pragma unroll
;     for (int q = 0; q < 4; ++q) {
;         float4 hv; hv.x = xv[q].x * r2 * gn[q].x; hv.y = xv[q].y * r2 * gn[q].y; hv.z = xv[q].z * r2 * gn[q].z; hv.w = xv[q].w * r2 * gn[q].w;
;         u32x2 w; w.x = pg8::cvt_pk_bf16(hv.x, hv.y); w.y = pg8::cvt_pk_bf16(hv.z, hv.w);
;         *(u32x2*)(XN + (size_t)row * 1024 + (q * 64 + lane) * 4) = w;
;         if (sh) *(float4*)(sh + (q * 64 + lane) * 4) = hv; }
; __device__ __forceinline__ void rows_phase(PR P, const int mode, LAS float* ldsf, const int wv) {
;     ...
;     if (gw < MP) {
;         const int last = gw + ((MP - 1 - gw) / nw) * nw;
;         RowRaw R, N;
;         rows_load(P, mode, gw, lane, R);
	v_lshlrev_b32_e32 v192, 16, v86
	v_and_b32_e32 v193, 0xffff0000, v86
	v_lshlrev_b32_e32 v194, 16, v87
	v_and_b32_e32 v195, 0xffff0000, v87
	v_add_f32_dpp v212, v212, v212 row_mirror row_mask:0xf bank_mask:0xf bound_ctrl:1
	s_nop 0
	v_readlane_b32 s20, v212, 0
	v_readlane_b32 s21, v212, 16
	v_readlane_b32 s22, v212, 32
	v_readlane_b32 s49, v212, 48
	s_nop 1
	v_mov_b32_e32 v212, s21
	v_add_f32_e32 v212, s20, v212
	v_add_f32_e32 v212, s22, v212
	v_add_f32_e32 v212, s49, v212
	v_fmamk_f32 v212, v212, 0x3a800000, v214
	v_rsq_f32_e32 v212, v212
	s_nop 0
	v_pk_mul_f32 v[196:197], v[212:213], v[196:197] op_sel_hi:[0,1]
	v_pk_mul_f32 v[198:199], v[212:213], v[198:199] op_sel_hi:[0,1]
	v_pk_mul_f32 v[200:201], v[212:213], v[200:201] op_sel_hi:[0,1]
	v_pk_mul_f32 v[202:203], v[212:213], v[202:203] op_sel_hi:[0,1]
	v_pk_mul_f32 v[204:205], v[212:213], v[204:205] op_sel_hi:[0,1]
	v_pk_mul_f32 v[206:207], v[212:213], v[206:207] op_sel_hi:[0,1]
	v_pk_mul_f32 v[208:209], v[212:213], v[208:209] op_sel_hi:[0,1]
	v_pk_mul_f32 v[210:211], v[212:213], v[210:211] op_sel_hi:[0,1]
	v_pk_fma_f32 v[180:181], v[0:1], v[196:197], v[180:181]
	v_pk_fma_f32 v[182:183], v[2:3], v[198:199], v[182:183]
	v_pk_fma_f32 v[184:185], v[4:5], v[200:201], v[184:185]
	v_pk_fma_f32 v[186:187], v[6:7], v[202:203], v[186:187]
	v_pk_fma_f32 v[188:189], v[8:9], v[204:205], v[188:189]
	v_pk_fma_f32 v[190:191], v[10:11], v[206:207], v[190:191]
	v_pk_fma_f32 v[192:193], v[12:13], v[208:209], v[192:193]
	v_pk_fma_f32 v[194:195], v[14:15], v[210:211], v[194:195]
	v_pk_mul_f32 v[212:213], v[180:181], v[180:181]
	v_pk_fma_f32 v[212:213], v[182:183], v[182:183], v[212:213]
	v_pk_fma_f32 v[212:213], v[184:185], v[184:185], v[212:213]
	v_pk_fma_f32 v[212:213], v[186:187], v[186:187], v[212:213]
	v_pk_fma_f32 v[212:213], v[188:189], v[188:189], v[212:213]
	v_pk_fma_f32 v[212:213], v[190:191], v[190:191], v[212:213]
	v_pk_fma_f32 v[212:213], v[192:193], v[192:193], v[212:213]
	v_pk_fma_f32 v[212:213], v[194:195], v[194:195], v[212:213]
	v_add_f32_e32 v212, v212, v213
	v_mov_b32_e32 v35, v36
	v_cvt_pk_bf16_f32 v216, v180, v181
	v_cvt_pk_bf16_f32 v217, v182, v183
	v_cvt_pk_bf16_f32 v218, v184, v185
	v_add_f32_dpp v212, v212, v212 quad_perm:[1,0,3,2] row_mask:0xf bank_mask:0xf bound_ctrl:1
	v_cvt_pk_bf16_f32 v219, v186, v187
	v_cvt_pk_bf16_f32 v220, v188, v189
	global_store_dwordx2 v35, v[216:217], s[14:15] offset:0 nt
	v_add_f32_dpp v212, v212, v212 quad_perm:[2,3,0,1] row_mask:0xf bank_mask:0xf bound_ctrl:1
	v_cvt_pk_bf16_f32 v221, v190, v191
	v_cvt_pk_bf16_f32 v222, v192, v193
	global_store_dwordx2 v35, v[218:219], s[14:15] offset:512 nt
	v_add_f32_dpp v212, v212, v212 row_half_mirror row_mask:0xf bank_mask:0xf bound_ctrl:1
	v_cvt_pk_bf16_f32 v223, v194, v195
	global_store_dwordx2 v35, v[220:221], s[14:15] offset:1024 nt
	global_store_dwordx2 v35, v[222:223], s[14:15] offset:1536 nt
	v_add_f32_dpp v212, v212, v212 row_mirror row_mask:0xf bank_mask:0xf bound_ctrl:1
	s_nop 0
	v_readlane_b32 s20, v212, 0
	v_readlane_b32 s21, v212, 16
	v_readlane_b32 s22, v212, 32
	v_readlane_b32 s49, v212, 48
	s_nop 1
	v_mov_b32_e32 v212, s21
	v_add_f32_e32 v212, s20, v212
	v_add_f32_e32 v212, s22, v212
	v_add_f32_e32 v212, s49, v212
	v_fmamk_f32 v212, v212, 0x3a800000, v214
	v_rsq_f32_e32 v212, v212
	s_nop 0
	v_pk_mul_f32 v[180:181], v[212:213], v[180:181] op_sel_hi:[0,1]
	v_pk_mul_f32 v[182:183], v[212:213], v[182:183] op_sel_hi:[0,1]
	v_pk_mul_f32 v[184:185], v[212:213], v[184:185] op_sel_hi:[0,1]
	v_pk_mul_f32 v[186:187], v[212:213], v[186:187] op_sel_hi:[0,1]
	v_pk_mul_f32 v[188:189], v[212:213], v[188:189] op_sel_hi:[0,1]
	v_pk_mul_f32 v[190:191], v[212:213], v[190:191] op_sel_hi:[0,1]
	v_pk_mul_f32 v[192:193], v[212:213], v[192:193] op_sel_hi:[0,1]
	v_pk_mul_f32 v[194:195], v[212:213], v[194:195] op_sel_hi:[0,1]
	v_pk_mul_f32 v[180:181], v[180:181], v[16:17]
	v_pk_mul_f32 v[182:183], v[182:183], v[18:19]
	v_pk_mul_f32 v[184:185], v[184:185], v[20:21]
	v_pk_mul_f32 v[186:187], v[186:187], v[22:23]
	v_pk_mul_f32 v[188:189], v[188:189], v[24:25]
	v_pk_mul_f32 v[190:191], v[190:191], v[26:27]
	v_pk_mul_f32 v[192:193], v[192:193], v[28:29]
	v_pk_mul_f32 v[194:195], v[194:195], v[30:31]
	v_cvt_pk_bf16_f32 v216, v180, v181
	v_cvt_pk_bf16_f32 v217, v182, v183
	v_cvt_pk_bf16_f32 v218, v184, v185
	v_cvt_pk_bf16_f32 v219, v186, v187
	v_cvt_pk_bf16_f32 v220, v188, v189
	v_cvt_pk_bf16_f32 v221, v190, v191
	v_cvt_pk_bf16_f32 v222, v192, v193
	v_cvt_pk_bf16_f32 v223, v194, v195
	global_store_dwordx2 v35, v[216:217], s[18:19] offset:0
	global_store_dwordx2 v35, v[218:219], s[18:19] offset:512
	global_store_dwordx2 v35, v[220:221], s[18:19] offset:1024
	global_store_dwordx2 v35, v[222:223], s[18:19] offset:1536
	v_add_u32_e32 v34, 0x1400000, v36
	global_load_dwordx2 v[80:81], v34, s[0:1] offset:0 nt
	global_load_dwordx2 v[82:83], v34, s[0:1] offset:512 nt
	global_load_dwordx2 v[84:85], v34, s[0:1] offset:1024 nt
	global_load_dwordx2 v[86:87], v34, s[0:1] offset:1536 nt
	global_load_dwordx2 v[88:89], v34, s[10:11] offset:0 nt
	global_load_dwordx2 v[90:91], v34, s[10:11] offset:512 nt
	global_load_dwordx2 v[92:93], v34, s[10:11] offset:1024 nt
	global_load_dwordx2 v[94:95], v34, s[10:11] offset:1536 nt
	s_waitcnt vmcnt(40)
; __device__ __forceinline__ unsigned cvt_pk_bf16(float lo, float hi) { const f32x2_t v = {lo, hi}; const bf16x2_t b = __builtin_convertvector(v, bf16x2_t); return __builtin_bit_cast(unsigned, b); }
; __device__ __forceinline__ void rows_proc(PR P, const int mode, const int row, const int lane, float4 (&xv)[4], const float4 (&fo)[4], const float4 (&gp)[4], const float4 (&gn)[4]) {
;     ...
;     if (mode != 0) {
;         float ss = 0.f;
; #pragma unroll
;         for (int q = 0; q < 4; ++q) ss += fo[q].x * fo[q].x + fo[q].y * fo[q].y + fo[q].z * fo[q].z + fo[q].w * fo[q].w;
;         ss = wave_sum(ss); const float r = rsqrtf(ss * (1.0f / 1024.0f) + 1e-6f) * (mode == 2 ? 1.0f : 0.5f);
; #pragma unroll
;         for (int q = 0; q < 4; ++q) {
;             xv[q].x += fo[q].x * r * gp[q].x; xv[q].y += fo[q].y * r * gp[q].y; xv[q].z += fo[q].z * r * gp[q].z; xv[q].w += fo[q].w * r * gp[q].w;
;             if (mode == 3) { const f32x4 t_ = {xv[q].x, xv[q].y, xv[q].z, xv[q].w}; __builtin_nontemporal_store(t_, (f32x4*)(P.out + (size_t)row * 1024 + (q * 64 + lane) * 4)); }
;             else { bf16_t* xo = (mode == 1 ? (bf16_t*)P.out : (bf16_t*)(P.ws + WS_FO + 34603008)) + (size_t)row * 1024; u32x2 t; t.x = pg8::cvt_pk_bf16(xv[q].x, xv[q].y); t.y = pg8::cvt_pk_bf16(xv[q].z, xv[q].w);
;                 __builtin_nontemporal_store(t, (u32x2*)(xo + (q * 64 + lane) * 4)); } }
;         if (mode == 3) return;
;     }
;     float ss2 = 0.f;
; #pragma unroll
;     for (int q = 0; q < 4; ++q) ss2 += xv[q].x * xv[q].x + xv[q].y * xv[q].y + xv[q].z * xv[q].z + xv[q].w * xv[q].w;
;     ss2 = wave_sum(ss2); const float r2 = rsqrtf(ss2 * (1.0f / 1024.0f) + 1e-6f);
;     float* sh = nullptr;
;     if (mode == 1) { if (row < MP) { if ((row & 2047) == 2047) sh = P.out + O_SHP + (size_t)(row >> 11) * 1024; } else { const int s = row - MP; if ((s & 3) == 3) sh = P.out + O_SHS + (size_t)(s >> 2) * 1024; } }
; #pragma unroll
;     for (int q = 0; q < 4; ++q) {
;         float4 hv; hv.x = xv[q].x * r2 * gn[q].x; hv.y = xv[q].y * r2 * gn[q].y; hv.z = xv[q].z * r2 * gn[q].z; hv.w = xv[q].w * r2 * gn[q].w;
;         u32x2 w; w.x = pg8::cvt_pk_bf16(hv.x, hv.y); w.y = pg8::cvt_pk_bf16(hv.z, hv.w);
;         *(u32x2*)(XN + (size_t)row * 1024 + (q * 64 + lane) * 4) = w;
;         if (sh) *(float4*)(sh + (q * 64 + lane) * 4) = hv; }
	v_lshlrev_b32_e32 v196, 16, v104
	v_and_b32_e32 v197, 0xffff0000, v104
	v_lshlrev_b32_e32 v198, 16, v105
	v_and_b32_e32 v199, 0xffff0000, v105
	v_lshlrev_b32_e32 v200, 16, v106
	v_and_b32_e32 v201, 0xffff0000, v106
	v_lshlrev_b32_e32 v202, 16, v107
	v_and_b32_e32 v203, 0xffff0000, v107
	v_lshlrev_b32_e32 v204, 16, v108
	v_and_b32_e32 v205, 0xffff0000, v108
	v_lshlrev_b32_e32 v206, 16, v109
	v_and_b32_e32 v207, 0xffff0000, v109
	v_lshlrev_b32_e32 v208, 16, v110
	v_and_b32_e32 v209, 0xffff0000, v110
	v_lshlrev_b32_e32 v210, 16, v111
	v_and_b32_e32 v211, 0xffff0000, v111
	v_pk_mul_f32 v[212:213], v[196:197], v[196:197]
	v_pk_fma_f32 v[212:213], v[198:199], v[198:199], v[212:213]
	v_pk_fma_f32 v[212:213], v[200:201], v[200:201], v[212:213]
	v_pk_fma_f32 v[212:213], v[202:203], v[202:203], v[212:213]
	v_pk_fma_f32 v[212:213], v[204:205], v[204:205], v[212:213]
	v_pk_fma_f32 v[212:213], v[206:207], v[206:207], v[212:213]
	v_pk_fma_f32 v[212:213], v[208:209], v[208:209], v[212:213]
	v_pk_fma_f32 v[212:213], v[210:211], v[210:211], v[212:213]
	v_add_f32_e32 v212, v212, v213
	v_lshlrev_b32_e32 v180, 16, v96
	v_and_b32_e32 v181, 0xffff0000, v96
	v_lshlrev_b32_e32 v182, 16, v97
	v_and_b32_e32 v183, 0xffff0000, v97
	v_add_f32_dpp v212, v212, v212 quad_perm:[1,0,3,2] row_mask:0xf bank_mask:0xf bound_ctrl:1
	v_lshlrev_b32_e32 v184, 16, v98
	v_and_b32_e32 v185, 0xffff0000, v98
	v_lshlrev_b32_e32 v186, 16, v99
	v_and_b32_e32 v187, 0xffff0000, v99
	v_add_f32_dpp v212, v212, v212 quad_perm:[2,3,0,1] row_mask:0xf bank_mask:0xf bound_ctrl:1
	v_lshlrev_b32_e32 v188, 16, v100
	v_and_b32_e32 v189, 0xffff0000, v100
	v_lshlrev_b32_e32 v190, 16, v101
	v_and_b32_e32 v191, 0xffff0000, v101
	v_add_f32_dpp v212, v212, v212 row_half_mirror row_mask:0xf bank_mask:0xf bound_ctrl:1
	v_lshlrev_b32_e32 v192, 16, v102
	v_and_b32_e32 v193, 0xffff0000, v102
	v_lshlrev_b32_e32 v194, 16, v103
	v_and_b32_e32 v195, 0xffff0000, v103
	v_add_f32_dpp v212, v212, v212 row_mirror row_mask:0xf bank_mask:0xf bound_ctrl:1
	s_nop 0
	v_readlane_b32 s20, v212, 0
	v_readlane_b32 s21, v212, 16
	v_readlane_b32 s22, v212, 32
	v_readlane_b32 s49, v212, 48
	s_nop 1
	v_mov_b32_e32 v212, s21
	v_add_f32_e32 v212, s20, v212
	v_add_f32_e32 v212, s22, v212
	v_add_f32_e32 v212, s49, v212
	v_fmamk_f32 v212, v212, 0x3a800000, v214
	v_rsq_f32_e32 v212, v212
	s_nop 0
	v_pk_mul_f32 v[196:197], v[212:213], v[196:197] op_sel_hi:[0,1]
	v_pk_mul_f32 v[198:199], v[212:213], v[198:199] op_sel_hi:[0,1]
	v_pk_mul_f32 v[200:201], v[212:213], v[200:201] op_sel_hi:[0,1]
	v_pk_mul_f32 v[202:203], v[212:213], v[202:203] op_sel_hi:[0,1]
	v_pk_mul_f32 v[204:205], v[212:213], v[204:205] op_sel_hi:[0,1]
	v_pk_mul_f32 v[206:207], v[212:213], v[206:207] op_sel_hi:[0,1]
	v_pk_mul_f32 v[208:209], v[212:213], v[208:209] op_sel_hi:[0,1]
	v_pk_mul_f32 v[210:211], v[212:213], v[210:211] op_sel_hi:[0,1]
	v_pk_fma_f32 v[180:181], v[0:1], v[196:197], v[180:181]
	v_pk_fma_f32 v[182:183], v[2:3], v[198:199], v[182:183]
	v_pk_fma_f32 v[184:185], v[4:5], v[200:201], v[184:185]
	v_pk_fma_f32 v[186:187], v[6:7], v[202:203], v[186:187]
	v_pk_fma_f32 v[188:189], v[8:9], v[204:205], v[188:189]
	v_pk_fma_f32 v[190:191], v[10:11], v[206:207], v[190:191]
	v_pk_fma_f32 v[192:193], v[12:13], v[208:209], v[192:193]
	v_pk_fma_f32 v[194:195], v[14:15], v[210:211], v[194:195]
	v_pk_mul_f32 v[212:213], v[180:181], v[180:181]
	v_pk_fma_f32 v[212:213], v[182:183], v[182:183], v[212:213]
	v_pk_fma_f32 v[212:213], v[184:185], v[184:185], v[212:213]
	v_pk_fma_f32 v[212:213], v[186:187], v[186:187], v[212:213]
	v_pk_fma_f32 v[212:213], v[188:189], v[188:189], v[212:213]
	v_pk_fma_f32 v[212:213], v[190:191], v[190:191], v[212:213]
	v_pk_fma_f32 v[212:213], v[192:193], v[192:193], v[212:213]
	v_pk_fma_f32 v[212:213], v[194:195], v[194:195], v[212:213]
	v_add_f32_e32 v212, v212, v213
	v_add_u32_e32 v35, 0x400000, v36
	v_cvt_pk_bf16_f32 v216, v180, v181
	v_cvt_pk_bf16_f32 v217, v182, v183
	v_cvt_pk_bf16_f32 v218, v184, v185
	v_add_f32_dpp v212, v212, v212 quad_perm:[1,0,3,2] row_mask:0xf bank_mask:0xf bound_ctrl:1
	v_cvt_pk_bf16_f32 v219, v186, v187
	v_cvt_pk_bf16_f32 v220, v188, v189
	global_store_dwordx2 v35, v[216:217], s[14:15] offset:0 nt
	v_add_f32_dpp v212, v212, v212 quad_perm:[2,3,0,1] row_mask:0xf bank_mask:0xf bound_ctrl:1
	v_cvt_pk_bf16_f32 v221, v190, v191
	v_cvt_pk_bf16_f32 v222, v192, v193
	global_store_dwordx2 v35, v[218:219], s[14:15] offset:512 nt
	v_add_f32_dpp v212, v212, v212 row_half_mirror row_mask:0xf bank_mask:0xf bound_ctrl:1
	v_cvt_pk_bf16_f32 v223, v194, v195
	global_store_dwordx2 v35, v[220:221], s[14:15] offset:1024 nt
	global_store_dwordx2 v35, v[222:223], s[14:15] offset:1536 nt
	v_add_f32_dpp v212, v212, v212 row_mirror row_mask:0xf bank_mask:0xf bound_ctrl:1
	s_nop 0
	v_readlane_b32 s20, v212, 0
	v_readlane_b32 s21, v212, 16
	v_readlane_b32 s22, v212, 32
	v_readlane_b32 s49, v212, 48
	s_nop 1
	v_mov_b32_e32 v212, s21
	v_add_f32_e32 v212, s20, v212
	v_add_f32_e32 v212, s22, v212
	v_add_f32_e32 v212, s49, v212
	v_fmamk_f32 v212, v212, 0x3a800000, v214
	v_rsq_f32_e32 v212, v212
	s_nop 0
	v_pk_mul_f32 v[180:181], v[212:213], v[180:181] op_sel_hi:[0,1]
	v_pk_mul_f32 v[182:183], v[212:213], v[182:183] op_sel_hi:[0,1]
	v_pk_mul_f32 v[184:185], v[212:213], v[184:185] op_sel_hi:[0,1]
	v_pk_mul_f32 v[186:187], v[212:213], v[186:187] op_sel_hi:[0,1]
	v_pk_mul_f32 v[188:189], v[212:213], v[188:189] op_sel_hi:[0,1]
	v_pk_mul_f32 v[190:191], v[212:213], v[190:191] op_sel_hi:[0,1]
	v_pk_mul_f32 v[192:193], v[212:213], v[192:193] op_sel_hi:[0,1]
	v_pk_mul_f32 v[194:195], v[212:213], v[194:195] op_sel_hi:[0,1]
	v_pk_mul_f32 v[180:181], v[180:181], v[16:17]
	v_pk_mul_f32 v[182:183], v[182:183], v[18:19]
	v_pk_mul_f32 v[184:185], v[184:185], v[20:21]
	v_pk_mul_f32 v[186:187], v[186:187], v[22:23]
	v_pk_mul_f32 v[188:189], v[188:189], v[24:25]
	v_pk_mul_f32 v[190:191], v[190:191], v[26:27]
	v_pk_mul_f32 v[192:193], v[192:193], v[28:29]
	v_pk_mul_f32 v[194:195], v[194:195], v[30:31]
	v_cvt_pk_bf16_f32 v216, v180, v181
	v_cvt_pk_bf16_f32 v217, v182, v183
	v_cvt_pk_bf16_f32 v218, v184, v185
	v_cvt_pk_bf16_f32 v219, v186, v187
	v_cvt_pk_bf16_f32 v220, v188, v189
	v_cvt_pk_bf16_f32 v221, v190, v191
	v_cvt_pk_bf16_f32 v222, v192, v193
	v_cvt_pk_bf16_f32 v223, v194, v195
	global_store_dwordx2 v35, v[216:217], s[18:19] offset:0
	global_store_dwordx2 v35, v[218:219], s[18:19] offset:512
	global_store_dwordx2 v35, v[220:221], s[18:19] offset:1024
	global_store_dwordx2 v35, v[222:223], s[18:19] offset:1536
	s_waitcnt vmcnt(47)
; __device__ __forceinline__ void rows_proc(PR P, const int mode, const int row, const int lane, float4 (&xv)[4], const float4 (&fo)[4], const float4 (&gp)[4], const float4 (&gn)[4]) {
;     ...
;     if (mode != 0) {
;         float ss = 0.f;
; #pragma unroll
;         for (int q = 0; q < 4; ++q) ss += fo[q].x * fo[q].x + fo[q].y * fo[q].y + fo[q].z * fo[q].z + fo[q].w * fo[q].w;
;         ss = wave_sum(ss); const float r = rsqrtf(ss * (1.0f / 1024.0f) + 1e-6f) * (mode == 2 ? 1.0f : 0.5f);
; #pragma unroll
;         for (int q = 0; q < 4; ++q) {
;             xv[q].x += fo[q].x * r * gp[q].x; xv[q].y += fo[q].y * r * gp[q].y; xv[q].z += fo[q].z * r * gp[q].z; xv[q].w += fo[q].w * r * gp[q].w;
;             if (mode == 3) { const f32x4 t_ = {xv[q].x, xv[q].y, xv[q].z, xv[q].w}; __builtin_nontemporal_store(t_, (f32x4*)(P.out + (size_t)row * 1024 + (q * 64 + lane) * 4)); }
;             else { bf16_t* xo = (mode == 1 ? (bf16_t*)P.out : (bf16_t*)(P.ws + WS_FO + 34603008)) + (size_t)row * 1024; u32x2 t; t.x = pg8::cvt_pk_bf16(xv[q].x, xv[q].y); t.y = pg8::cvt_pk_bf16(xv[q].z, xv[q].w);
;                 __builtin_nontemporal_store(t, (u32x2*)(xo + (q * 64 + lane) * 4)); } }
;         if (mode == 3) return;
;     }
;     float ss2 = 0.f;
; #pragma unroll
;     for (int q = 0; q < 4; ++q) ss2 += xv[q].x * xv[q].x + xv[q].y * xv[q].y + xv[q].z * xv[q].z + xv[q].w * xv[q].w;
;     ss2 = wave_sum(ss2); const float r2 = rsqrtf(ss2 * (1.0f / 1024.0f) + 1e-6f);
;     float* sh = nullptr;
;     if (mode == 1) { if (row < MP) { if ((row & 2047) == 2047) sh = P.out + O_SHP + (size_t)(row >> 11) * 1024; } else { const int s = row - MP; if ((s & 3) == 3) sh = P.out + O_SHS + (size_t)(s >> 2) * 1024; } }
; #pragma unroll
;     for (int q = 0; q < 4; ++q) {
;         float4 hv; hv.x = xv[q].x * r2 * gn[q].x; hv.y = xv[q].y * r2 * gn[q].y; hv.z = xv[q].z * r2 * gn[q].z; hv.w = xv[q].w * r2 * gn[q].w;
;         u32x2 w; w.x = pg8::cvt_pk_bf16(hv.x, hv.y); w.y = pg8::cvt_pk_bf16(hv.z, hv.w);
;         *(u32x2*)(XN + (size_t)row * 1024 + (q * 64 + lane) * 4) = w;
;         if (sh) *(float4*)(sh + (q * 64 + lane) * 4) = hv; }
; __device__ __forceinline__ void rows_phase(PR P, const int mode, LAS float* ldsf, const int wv) {
;     ...
;         for (int row = gw; row < MP; row += nw) {
;             const int nrow = row + nw < MP ? row + nw : last;
;             rows_load(P, mode, nrow, lane, N);
	v_add_u32_e32 v34, 0x1800000, v36
	global_load_dwordx2 v[96:97], v34, s[0:1] offset:0 nt
	global_load_dwordx2 v[98:99], v34, s[0:1] offset:512 nt
	global_load_dwordx2 v[100:101], v34, s[0:1] offset:1024 nt
	global_load_dwordx2 v[102:103], v34, s[0:1] offset:1536 nt
	global_load_dwordx2 v[104:105], v34, s[10:11] offset:0 nt
	global_load_dwordx2 v[106:107], v34, s[10:11] offset:512 nt
	global_load_dwordx2 v[108:109], v34, s[10:11] offset:1024 nt
	global_load_dwordx2 v[110:111], v34, s[10:11] offset:1536 nt
	s_waitcnt vmcnt(48)
	v_lshlrev_b32_e32 v196, 16, v120
	v_and_b32_e32 v197, 0xffff0000, v120
	v_lshlrev_b32_e32 v198, 16, v121
	v_and_b32_e32 v199, 0xffff0000, v121
	v_lshlrev_b32_e32 v200, 16, v122
	v_and_b32_e32 v201, 0xffff0000, v122
	v_lshlrev_b32_e32 v202, 16, v123
	v_and_b32_e32 v203, 0xffff0000, v123
	v_lshlrev_b32_e32 v204, 16, v124
	v_and_b32_e32 v205, 0xffff0000, v124
	v_lshlrev_b32_e32 v206, 16, v125
	v_and_b32_e32 v207, 0xffff0000, v125
	v_lshlrev_b32_e32 v208, 16, v126
	v_and_b32_e32 v209, 0xffff0000, v126
	v_lshlrev_b32_e32 v210, 16, v127
	v_and_b32_e32 v211, 0xffff0000, v127
	v_pk_mul_f32 v[212:213], v[196:197], v[196:197]
	v_pk_fma_f32 v[212:213], v[198:199], v[198:199], v[212:213]
	v_pk_fma_f32 v[212:213], v[200:201], v[200:201], v[212:213]
	v_pk_fma_f32 v[212:213], v[202:203], v[202:203], v[212:213]
	v_pk_fma_f32 v[212:213], v[204:205], v[204:205], v[212:213]
	v_pk_fma_f32 v[212:213], v[206:207], v[206:207], v[212:213]
	v_pk_fma_f32 v[212:213], v[208:209], v[208:209], v[212:213]
	v_pk_fma_f32 v[212:213], v[210:211], v[210:211], v[212:213]
	v_add_f32_e32 v212, v212, v213
	v_lshlrev_b32_e32 v180, 16, v112
	v_and_b32_e32 v181, 0xffff0000, v112
	v_lshlrev_b32_e32 v182, 16, v113
	v_and_b32_e32 v183, 0xffff0000, v113
	v_add_f32_dpp v212, v212, v212 quad_perm:[1,0,3,2] row_mask:0xf bank_mask:0xf bound_ctrl:1
	v_lshlrev_b32_e32 v184, 16, v114
	v_and_b32_e32 v185, 0xffff0000, v114
	v_lshlrev_b32_e32 v186, 16, v115
	v_and_b32_e32 v187, 0xffff0000, v115
	v_add_f32_dpp v212, v212, v212 quad_perm:[2,3,0,1] row_mask:0xf bank_mask:0xf bound_ctrl:1
	v_lshlrev_b32_e32 v188, 16, v116
	v_and_b32_e32 v189, 0xffff0000, v116
	v_lshlrev_b32_e32 v190, 16, v117
	v_and_b32_e32 v191, 0xffff0000, v117
	v_add_f32_dpp v212, v212, v212 row_half_mirror row_mask:0xf bank_mask:0xf bound_ctrl:1
	v_lshlrev_b32_e32 v192, 16, v118
	v_and_b32_e32 v193, 0xffff0000, v118
	v_lshlrev_b32_e32 v194, 16, v119
	v_and_b32_e32 v195, 0xffff0000, v119
	v_add_f32_dpp v212, v212, v212 row_mirror row_mask:0xf bank_mask:0xf bound_ctrl:1
	s_nop 0
	v_readlane_b32 s20, v212, 0
	v_readlane_b32 s21, v212, 16
	v_readlane_b32 s22, v212, 32
	v_readlane_b32 s49, v212, 48
	s_nop 1
	v_mov_b32_e32 v212, s21
	v_add_f32_e32 v212, s20, v212
	v_add_f32_e32 v212, s22, v212
	v_add_f32_e32 v212, s49, v212
	v_fmamk_f32 v212, v212, 0x3a800000, v214
	v_rsq_f32_e32 v212, v212
	s_nop 0
	v_pk_mul_f32 v[196:197], v[212:213], v[196:197] op_sel_hi:[0,1]
	v_pk_mul_f32 v[198:199], v[212:213], v[198:199] op_sel_hi:[0,1]
	v_pk_mul_f32 v[200:201], v[212:213], v[200:201] op_sel_hi:[0,1]
	v_pk_mul_f32 v[202:203], v[212:213], v[202:203] op_sel_hi:[0,1]
	v_pk_mul_f32 v[204:205], v[212:213], v[204:205] op_sel_hi:[0,1]
	v_pk_mul_f32 v[206:207], v[212:213], v[206:207] op_sel_hi:[0,1]
	v_pk_mul_f32 v[208:209], v[212:213], v[208:209] op_sel_hi:[0,1]
	v_pk_mul_f32 v[210:211], v[212:213], v[210:211] op_sel_hi:[0,1]
	v_pk_fma_f32 v[180:181], v[0:1], v[196:197], v[180:181]
	v_pk_fma_f32 v[182:183], v[2:3], v[198:199], v[182:183]
	v_pk_fma_f32 v[184:185], v[4:5], v[200:201], v[184:185]
	v_pk_fma_f32 v[186:187], v[6:7], v[202:203], v[186:187]
	v_pk_fma_f32 v[188:189], v[8:9], v[204:205], v[188:189]
	v_pk_fma_f32 v[190:191], v[10:11], v[206:207], v[190:191]
	v_pk_fma_f32 v[192:193], v[12:13], v[208:209], v[192:193]
	v_pk_fma_f32 v[194:195], v[14:15], v[210:211], v[194:195]
	v_pk_mul_f32 v[212:213], v[180:181], v[180:181]
	v_pk_fma_f32 v[212:213], v[182:183], v[182:183], v[212:213]
	v_pk_fma_f32 v[212:213], v[184:185], v[184:185], v[212:213]
	v_pk_fma_f32 v[212:213], v[186:187], v[186:187], v[212:213]
	v_pk_fma_f32 v[212:213], v[188:189], v[188:189], v[212:213]
	v_pk_fma_f32 v[212:213], v[190:191], v[190:191], v[212:213]
	v_pk_fma_f32 v[212:213], v[192:193], v[192:193], v[212:213]
	v_pk_fma_f32 v[212:213], v[194:195], v[194:195], v[212:213]
	v_add_f32_e32 v212, v212, v213
	v_add_u32_e32 v35, 0x800000, v36
	v_cvt_pk_bf16_f32 v216, v180, v181
	v_cvt_pk_bf16_f32 v217, v182, v183
	v_cvt_pk_bf16_f32 v218, v184, v185
	v_add_f32_dpp v212, v212, v212 quad_perm:[1,0,3,2] row_mask:0xf bank_mask:0xf bound_ctrl:1
	v_cvt_pk_bf16_f32 v219, v186, v187
	v_cvt_pk_bf16_f32 v220, v188, v189
	global_store_dwordx2 v35, v[216:217], s[14:15] offset:0 nt
	v_add_f32_dpp v212, v212, v212 quad_perm:[2,3,0,1] row_mask:0xf bank_mask:0xf bound_ctrl:1
	v_cvt_pk_bf16_f32 v221, v190, v191
	v_cvt_pk_bf16_f32 v222, v192, v193
	global_store_dwordx2 v35, v[218:219], s[14:15] offset:512 nt
	v_add_f32_dpp v212, v212, v212 row_half_mirror row_mask:0xf bank_mask:0xf bound_ctrl:1
	v_cvt_pk_bf16_f32 v223, v194, v195
	global_store_dwordx2 v35, v[220:221], s[14:15] offset:1024 nt
	global_store_dwordx2 v35, v[222:223], s[14:15] offset:1536 nt
	v_add_f32_dpp v212, v212, v212 row_mirror row_mask:0xf bank_mask:0xf bound_ctrl:1
	s_nop 0
	v_readlane_b32 s20, v212, 0
	v_readlane_b32 s21, v212, 16
	v_readlane_b32 s22, v212, 32
	v_readlane_b32 s49, v212, 48
	s_nop 1
	v_mov_b32_e32 v212, s21
	v_add_f32_e32 v212, s20, v212
	v_add_f32_e32 v212, s22, v212
	v_add_f32_e32 v212, s49, v212
	v_fmamk_f32 v212, v212, 0x3a800000, v214
	v_rsq_f32_e32 v212, v212
	s_nop 0
; __device__ __forceinline__ void rows_proc(PR P, const int mode, const int row, const int lane, float4 (&xv)[4], const float4 (&fo)[4], const float4 (&gp)[4], const float4 (&gn)[4]) {
;     ...
;     if (mode != 0) {
;         float ss = 0.f;
; #pragma unroll
;         for (int q = 0; q < 4; ++q) ss += fo[q].x * fo[q].x + fo[q].y * fo[q].y + fo[q].z * fo[q].z + fo[q].w * fo[q].w;
;         ss = wave_sum(ss); const float r = rsqrtf(ss * (1.0f / 1024.0f) + 1e-6f) * (mode == 2 ? 1.0f : 0.5f);
; #pragma unroll
;         for (int q = 0; q < 4; ++q) {
;             xv[q].x += fo[q].x * r * gp[q].x; xv[q].y += fo[q].y * r * gp[q].y; xv[q].z += fo[q].z * r * gp[q].z; xv[q].w += fo[q].w * r * gp[q].w;
;             if (mode == 3) { const f32x4 t_ = {xv[q].x, xv[q].y, xv[q].z, xv[q].w}; __builtin_nontemporal_store(t_, (f32x4*)(P.out + (size_t)row * 1024 + (q * 64 + lane) * 4)); }
;             else { bf16_t* xo = (mode == 1 ? (bf16_t*)P.out : (bf16_t*)(P.ws + WS_FO + 34603008)) + (size_t)row * 1024; u32x2 t; t.x = pg8::cvt_pk_bf16(xv[q].x, xv[q].y); t.y = pg8::cvt_pk_bf16(xv[q].z, xv[q].w);
;                 __builtin_nontemporal_store(t, (u32x2*)(xo + (q * 64 + lane) * 4)); } }
;         if (mode == 3) return;
;     }
;     float ss2 = 0.f;
; #pragma unroll
;     for (int q = 0; q < 4; ++q) ss2 += xv[q].x * xv[q].x + xv[q].y * xv[q].y + xv[q].z * xv[q].z + xv[q].w * xv[q].w;
;     ss2 = wave_sum(ss2); const float r2 = rsqrtf(ss2 * (1.0f / 1024.0f) + 1e-6f);
;     float* sh = nullptr;
;     if (mode == 1) { if (row < MP) { if ((row & 2047) == 2047) sh = P.out + O_SHP + (size_t)(row >> 11) * 1024; } else { const int s = row - MP; if ((s & 3) == 3) sh = P.out + O_SHS + (size_t)(s >> 2) * 1024; } }
; #pragma unroll
;     for (int q = 0; q < 4; ++q) {
;         float4 hv; hv.x = xv[q].x * r2 * gn[q].x; hv.y = xv[q].y * r2 * gn[q].y; hv.z = xv[q].z * r2 * gn[q].z; hv.w = xv[q].w * r2 * gn[q].w;
;         u32x2 w; w.x = pg8::cvt_pk_bf16(hv.x, hv.y); w.y = pg8::cvt_pk_bf16(hv.z, hv.w);
;         *(u32x2*)(XN + (size_t)row * 1024 + (q * 64 + lane) * 4) = w;
;         if (sh) *(float4*)(sh + (q * 64 + lane) * 4) = hv; }
; __device__ __forceinline__ void rows_phase(PR P, const int mode, LAS float* ldsf, const int wv) {
;     ...
;         for (int row = gw; row < MP; row += nw) {
;             const int nrow = row + nw < MP ? row + nw : last;
;             rows_load(P, mode, nrow, lane, N);
	v_pk_mul_f32 v[180:181], v[212:213], v[180:181] op_sel_hi:[0,1]
	v_pk_mul_f32 v[182:183], v[212:213], v[182:183] op_sel_hi:[0,1]
	v_pk_mul_f32 v[184:185], v[212:213], v[184:185] op_sel_hi:[0,1]
	v_pk_mul_f32 v[186:187], v[212:213], v[186:187] op_sel_hi:[0,1]
	v_pk_mul_f32 v[188:189], v[212:213], v[188:189] op_sel_hi:[0,1]
	v_pk_mul_f32 v[190:191], v[212:213], v[190:191] op_sel_hi:[0,1]
	v_pk_mul_f32 v[192:193], v[212:213], v[192:193] op_sel_hi:[0,1]
	v_pk_mul_f32 v[194:195], v[212:213], v[194:195] op_sel_hi:[0,1]
	v_pk_mul_f32 v[180:181], v[180:181], v[16:17]
	v_pk_mul_f32 v[182:183], v[182:183], v[18:19]
	v_pk_mul_f32 v[184:185], v[184:185], v[20:21]
	v_pk_mul_f32 v[186:187], v[186:187], v[22:23]
	v_pk_mul_f32 v[188:189], v[188:189], v[24:25]
	v_pk_mul_f32 v[190:191], v[190:191], v[26:27]
	v_pk_mul_f32 v[192:193], v[192:193], v[28:29]
	v_pk_mul_f32 v[194:195], v[194:195], v[30:31]
	v_cvt_pk_bf16_f32 v216, v180, v181
	v_cvt_pk_bf16_f32 v217, v182, v183
	v_cvt_pk_bf16_f32 v218, v184, v185
	v_cvt_pk_bf16_f32 v219, v186, v187
	v_cvt_pk_bf16_f32 v220, v188, v189
	v_cvt_pk_bf16_f32 v221, v190, v191
	v_cvt_pk_bf16_f32 v222, v192, v193
	v_cvt_pk_bf16_f32 v223, v194, v195
	global_store_dwordx2 v35, v[216:217], s[18:19] offset:0
	global_store_dwordx2 v35, v[218:219], s[18:19] offset:512
	global_store_dwordx2 v35, v[220:221], s[18:19] offset:1024
	global_store_dwordx2 v35, v[222:223], s[18:19] offset:1536
	s_waitcnt vmcnt(47)
	v_add_u32_e32 v34, 0x1c00000, v36
	global_load_dwordx2 v[112:113], v34, s[0:1] offset:0 nt
	global_load_dwordx2 v[114:115], v34, s[0:1] offset:512 nt
	global_load_dwordx2 v[116:117], v34, s[0:1] offset:1024 nt
	global_load_dwordx2 v[118:119], v34, s[0:1] offset:1536 nt
	global_load_dwordx2 v[120:121], v34, s[10:11] offset:0 nt
	global_load_dwordx2 v[122:123], v34, s[10:11] offset:512 nt
	global_load_dwordx2 v[124:125], v34, s[10:11] offset:1024 nt
	global_load_dwordx2 v[126:127], v34, s[10:11] offset:1536 nt
	v_lshlrev_b32_e32 v196, 16, v136
	v_and_b32_e32 v197, 0xffff0000, v136
	v_lshlrev_b32_e32 v198, 16, v137
	v_and_b32_e32 v199, 0xffff0000, v137
	v_lshlrev_b32_e32 v200, 16, v138
	v_and_b32_e32 v201, 0xffff0000, v138
	v_lshlrev_b32_e32 v202, 16, v139
	v_and_b32_e32 v203, 0xffff0000, v139
	v_lshlrev_b32_e32 v204, 16, v140
	v_and_b32_e32 v205, 0xffff0000, v140
	v_lshlrev_b32_e32 v206, 16, v141
	v_and_b32_e32 v207, 0xffff0000, v141
	v_lshlrev_b32_e32 v208, 16, v142
	v_and_b32_e32 v209, 0xffff0000, v142
	v_lshlrev_b32_e32 v210, 16, v143
	v_and_b32_e32 v211, 0xffff0000, v143
	v_pk_mul_f32 v[212:213], v[196:197], v[196:197]
	v_pk_fma_f32 v[212:213], v[198:199], v[198:199], v[212:213]
	v_pk_fma_f32 v[212:213], v[200:201], v[200:201], v[212:213]
	v_pk_fma_f32 v[212:213], v[202:203], v[202:203], v[212:213]
	v_pk_fma_f32 v[212:213], v[204:205], v[204:205], v[212:213]
	v_pk_fma_f32 v[212:213], v[206:207], v[206:207], v[212:213]
	v_pk_fma_f32 v[212:213], v[208:209], v[208:209], v[212:213]
	v_pk_fma_f32 v[212:213], v[210:211], v[210:211], v[212:213]
	v_add_f32_e32 v212, v212, v213
	v_lshlrev_b32_e32 v180, 16, v128
	v_and_b32_e32 v181, 0xffff0000, v128
	v_lshlrev_b32_e32 v182, 16, v129
	v_and_b32_e32 v183, 0xffff0000, v129
	v_add_f32_dpp v212, v212, v212 quad_perm:[1,0,3,2] row_mask:0xf bank_mask:0xf bound_ctrl:1
	v_lshlrev_b32_e32 v184, 16, v130
	v_and_b32_e32 v185, 0xffff0000, v130
	v_lshlrev_b32_e32 v186, 16, v131
	v_and_b32_e32 v187, 0xffff0000, v131
	v_add_f32_dpp v212, v212, v212 quad_perm:[2,3,0,1] row_mask:0xf bank_mask:0xf bound_ctrl:1
	v_lshlrev_b32_e32 v188, 16, v132
	v_and_b32_e32 v189, 0xffff0000, v132
	v_lshlrev_b32_e32 v190, 16, v133
	v_and_b32_e32 v191, 0xffff0000, v133
	v_add_f32_dpp v212, v212, v212 row_half_mirror row_mask:0xf bank_mask:0xf bound_ctrl:1
	v_lshlrev_b32_e32 v192, 16, v134
	v_and_b32_e32 v193, 0xffff0000, v134
	v_lshlrev_b32_e32 v194, 16, v135
	v_and_b32_e32 v195, 0xffff0000, v135
	v_add_f32_dpp v212, v212, v212 row_mirror row_mask:0xf bank_mask:0xf bound_ctrl:1
	s_nop 0
	v_readlane_b32 s20, v212, 0
	v_readlane_b32 s21, v212, 16
	v_readlane_b32 s22, v212, 32
	v_readlane_b32 s49, v212, 48
	s_nop 1
	v_mov_b32_e32 v212, s21
	v_add_f32_e32 v212, s20, v212
	v_add_f32_e32 v212, s22, v212
	v_add_f32_e32 v212, s49, v212
	v_fmamk_f32 v212, v212, 0x3a800000, v214
	v_rsq_f32_e32 v212, v212
	s_nop 0
	v_pk_mul_f32 v[196:197], v[212:213], v[196:197] op_sel_hi:[0,1]
	v_pk_mul_f32 v[198:199], v[212:213], v[198:199] op_sel_hi:[0,1]
	v_pk_mul_f32 v[200:201], v[212:213], v[200:201] op_sel_hi:[0,1]
	v_pk_mul_f32 v[202:203], v[212:213], v[202:203] op_sel_hi:[0,1]
	v_pk_mul_f32 v[204:205], v[212:213], v[204:205] op_sel_hi:[0,1]
	v_pk_mul_f32 v[206:207], v[212:213], v[206:207] op_sel_hi:[0,1]
	v_pk_mul_f32 v[208:209], v[212:213], v[208:209] op_sel_hi:[0,1]
	v_pk_mul_f32 v[210:211], v[212:213], v[210:211] op_sel_hi:[0,1]
	v_pk_fma_f32 v[180:181], v[0:1], v[196:197], v[180:181]
	v_pk_fma_f32 v[182:183], v[2:3], v[198:199], v[182:183]
	v_pk_fma_f32 v[184:185], v[4:5], v[200:201], v[184:185]
	v_pk_fma_f32 v[186:187], v[6:7], v[202:203], v[186:187]
	v_pk_fma_f32 v[188:189], v[8:9], v[204:205], v[188:189]
	v_pk_fma_f32 v[190:191], v[10:11], v[206:207], v[190:191]
	v_pk_fma_f32 v[192:193], v[12:13], v[208:209], v[192:193]
	v_pk_fma_f32 v[194:195], v[14:15], v[210:211], v[194:195]
	v_pk_mul_f32 v[212:213], v[180:181], v[180:181]
	v_pk_fma_f32 v[212:213], v[182:183], v[182:183], v[212:213]
	v_pk_fma_f32 v[212:213], v[184:185], v[184:185], v[212:213]
	v_pk_fma_f32 v[212:213], v[186:187], v[186:187], v[212:213]
	v_pk_fma_f32 v[212:213], v[188:189], v[188:189], v[212:213]
	v_pk_fma_f32 v[212:213], v[190:191], v[190:191], v[212:213]
; __device__ __forceinline__ unsigned cvt_pk_bf16(float lo, float hi) { const f32x2_t v = {lo, hi}; const bf16x2_t b = __builtin_convertvector(v, bf16x2_t); return __builtin_bit_cast(unsigned, b); }
; __device__ __forceinline__ void rows_proc(PR P, const int mode, const int row, const int lane, float4 (&xv)[4], const float4 (&fo)[4], const float4 (&gp)[4], const float4 (&gn)[4]) {
;     ...
;     if (mode != 0) {
;         float ss = 0.f;
; #pragma unroll
;         for (int q = 0; q < 4; ++q) ss += fo[q].x * fo[q].x + fo[q].y * fo[q].y + fo[q].z * fo[q].z + fo[q].w * fo[q].w;
;         ss = wave_sum(ss); const float r = rsqrtf(ss * (1.0f / 1024.0f) + 1e-6f) * (mode == 2 ? 1.0f : 0.5f);
; #pragma unroll
;         for (int q = 0; q < 4; ++q) {
;             xv[q].x += fo[q].x * r * gp[q].x; xv[q].y += fo[q].y * r * gp[q].y; xv[q].z += fo[q].z * r * gp[q].z; xv[q].w += fo[q].w * r * gp[q].w;
;             if (mode == 3) { const f32x4 t_ = {xv[q].x, xv[q].y, xv[q].z, xv[q].w}; __builtin_nontemporal_store(t_, (f32x4*)(P.out + (size_t)row * 1024 + (q * 64 + lane) * 4)); }
;             else { bf16_t* xo = (mode == 1 ? (bf16_t*)P.out : (bf16_t*)(P.ws + WS_FO + 34603008)) + (size_t)row * 1024; u32x2 t; t.x = pg8::cvt_pk_bf16(xv[q].x, xv[q].y); t.y = pg8::cvt_pk_bf16(xv[q].z, xv[q].w);
;                 __builtin_nontemporal_store(t, (u32x2*)(xo + (q * 64 + lane) * 4)); } }
;         if (mode == 3) return;
;     }
;     float ss2 = 0.f;
; #pragma unroll
;     for (int q = 0; q < 4; ++q) ss2 += xv[q].x * xv[q].x + xv[q].y * xv[q].y + xv[q].z * xv[q].z + xv[q].w * xv[q].w;
;     ss2 = wave_sum(ss2); const float r2 = rsqrtf(ss2 * (1.0f / 1024.0f) + 1e-6f);
;     float* sh = nullptr;
;     if (mode == 1) { if (row < MP) { if ((row & 2047) == 2047) sh = P.out + O_SHP + (size_t)(row >> 11) * 1024; } else { const int s = row - MP; if ((s & 3) == 3) sh = P.out + O_SHS + (size_t)(s >> 2) * 1024; } }
; #pragma unroll
;     for (int q = 0; q < 4; ++q) {
;         float4 hv; hv.x = xv[q].x * r2 * gn[q].x; hv.y = xv[q].y * r2 * gn[q].y; hv.z = xv[q].z * r2 * gn[q].z; hv.w = xv[q].w * r2 * gn[q].w;
;         u32x2 w; w.x = pg8::cvt_pk_bf16(hv.x, hv.y); w.y = pg8::cvt_pk_bf16(hv.z, hv.w);
;         *(u32x2*)(XN + (size_t)row * 1024 + (q * 64 + lane) * 4) = w;
;         if (sh) *(float4*)(sh + (q * 64 + lane) * 4) = hv; }
	v_pk_fma_f32 v[212:213], v[192:193], v[192:193], v[212:213]
	v_pk_fma_f32 v[212:213], v[194:195], v[194:195], v[212:213]
	v_add_f32_e32 v212, v212, v213
	v_add_u32_e32 v35, 0xc00000, v36
	v_cvt_pk_bf16_f32 v216, v180, v181
	v_cvt_pk_bf16_f32 v217, v182, v183
	v_cvt_pk_bf16_f32 v218, v184, v185
	v_add_f32_dpp v212, v212, v212 quad_perm:[1,0,3,2] row_mask:0xf bank_mask:0xf bound_ctrl:1
	v_cvt_pk_bf16_f32 v219, v186, v187
	v_cvt_pk_bf16_f32 v220, v188, v189
	global_store_dwordx2 v35, v[216:217], s[14:15] offset:0 nt
	v_add_f32_dpp v212, v212, v212 quad_perm:[2,3,0,1] row_mask:0xf bank_mask:0xf bound_ctrl:1
	v_cvt_pk_bf16_f32 v221, v190, v191
	v_cvt_pk_bf16_f32 v222, v192, v193
	global_store_dwordx2 v35, v[218:219], s[14:15] offset:512 nt
	v_add_f32_dpp v212, v212, v212 row_half_mirror row_mask:0xf bank_mask:0xf bound_ctrl:1
	v_cvt_pk_bf16_f32 v223, v194, v195
	global_store_dwordx2 v35, v[220:221], s[14:15] offset:1024 nt
	global_store_dwordx2 v35, v[222:223], s[14:15] offset:1536 nt
	v_add_f32_dpp v212, v212, v212 row_mirror row_mask:0xf bank_mask:0xf bound_ctrl:1
	s_nop 0
	v_readlane_b32 s20, v212, 0
	v_readlane_b32 s21, v212, 16
	v_readlane_b32 s22, v212, 32
	v_readlane_b32 s49, v212, 48
	s_nop 1
	v_mov_b32_e32 v212, s21
	v_add_f32_e32 v212, s20, v212
	v_add_f32_e32 v212, s22, v212
	v_add_f32_e32 v212, s49, v212
	v_fmamk_f32 v212, v212, 0x3a800000, v214
	v_rsq_f32_e32 v212, v212
	s_nop 0
	v_pk_mul_f32 v[180:181], v[212:213], v[180:181] op_sel_hi:[0,1]
	v_pk_mul_f32 v[182:183], v[212:213], v[182:183] op_sel_hi:[0,1]
	v_pk_mul_f32 v[184:185], v[212:213], v[184:185] op_sel_hi:[0,1]
	v_pk_mul_f32 v[186:187], v[212:213], v[186:187] op_sel_hi:[0,1]
	v_pk_mul_f32 v[188:189], v[212:213], v[188:189] op_sel_hi:[0,1]
	v_pk_mul_f32 v[190:191], v[212:213], v[190:191] op_sel_hi:[0,1]
	v_pk_mul_f32 v[192:193], v[212:213], v[192:193] op_sel_hi:[0,1]
	v_pk_mul_f32 v[194:195], v[212:213], v[194:195] op_sel_hi:[0,1]
	v_pk_mul_f32 v[180:181], v[180:181], v[16:17]
	v_pk_mul_f32 v[182:183], v[182:183], v[18:19]
	v_pk_mul_f32 v[184:185], v[184:185], v[20:21]
	v_pk_mul_f32 v[186:187], v[186:187], v[22:23]
	v_pk_mul_f32 v[188:189], v[188:189], v[24:25]
	v_pk_mul_f32 v[190:191], v[190:191], v[26:27]
	v_pk_mul_f32 v[192:193], v[192:193], v[28:29]
	v_pk_mul_f32 v[194:195], v[194:195], v[30:31]
	v_cvt_pk_bf16_f32 v216, v180, v181
	v_cvt_pk_bf16_f32 v217, v182, v183
	v_cvt_pk_bf16_f32 v218, v184, v185
	v_cvt_pk_bf16_f32 v219, v186, v187
	v_cvt_pk_bf16_f32 v220, v188, v189
	v_cvt_pk_bf16_f32 v221, v190, v191
	v_cvt_pk_bf16_f32 v222, v192, v193
	v_cvt_pk_bf16_f32 v223, v194, v195
	global_store_dwordx2 v35, v[216:217], s[18:19] offset:0
	global_store_dwordx2 v35, v[218:219], s[18:19] offset:512
	global_store_dwordx2 v35, v[220:221], s[18:19] offset:1024
	global_store_dwordx2 v35, v[222:223], s[18:19] offset:1536
	s_waitcnt vmcnt(48)
	v_lshlrev_b32_e32 v196, 16, v152
	v_and_b32_e32 v197, 0xffff0000, v152
	v_lshlrev_b32_e32 v198, 16, v153
	v_and_b32_e32 v199, 0xffff0000, v153
	v_lshlrev_b32_e32 v200, 16, v154
	v_and_b32_e32 v201, 0xffff0000, v154
	v_lshlrev_b32_e32 v202, 16, v155
	v_and_b32_e32 v203, 0xffff0000, v155
	v_lshlrev_b32_e32 v204, 16, v156
	v_and_b32_e32 v205, 0xffff0000, v156
	v_lshlrev_b32_e32 v206, 16, v157
	v_and_b32_e32 v207, 0xffff0000, v157
	v_lshlrev_b32_e32 v208, 16, v158
	v_and_b32_e32 v209, 0xffff0000, v158
	v_lshlrev_b32_e32 v210, 16, v159
	v_and_b32_e32 v211, 0xffff0000, v159
	v_pk_mul_f32 v[212:213], v[196:197], v[196:197]
	v_pk_fma_f32 v[212:213], v[198:199], v[198:199], v[212:213]
	v_pk_fma_f32 v[212:213], v[200:201], v[200:201], v[212:213]
	v_pk_fma_f32 v[212:213], v[202:203], v[202:203], v[212:213]
	v_pk_fma_f32 v[212:213], v[204:205], v[204:205], v[212:213]
	v_pk_fma_f32 v[212:213], v[206:207], v[206:207], v[212:213]
	v_pk_fma_f32 v[212:213], v[208:209], v[208:209], v[212:213]
	v_pk_fma_f32 v[212:213], v[210:211], v[210:211], v[212:213]
	v_add_f32_e32 v212, v212, v213
	v_lshlrev_b32_e32 v180, 16, v144
	v_and_b32_e32 v181, 0xffff0000, v144
	v_lshlrev_b32_e32 v182, 16, v145
	v_and_b32_e32 v183, 0xffff0000, v145
	v_add_f32_dpp v212, v212, v212 quad_perm:[1,0,3,2] row_mask:0xf bank_mask:0xf bound_ctrl:1
	v_lshlrev_b32_e32 v184, 16, v146
	v_and_b32_e32 v185, 0xffff0000, v146
	v_lshlrev_b32_e32 v186, 16, v147
	v_and_b32_e32 v187, 0xffff0000, v147
	v_add_f32_dpp v212, v212, v212 quad_perm:[2,3,0,1] row_mask:0xf bank_mask:0xf bound_ctrl:1
	v_lshlrev_b32_e32 v188, 16, v148
	v_and_b32_e32 v189, 0xffff0000, v148
	v_lshlrev_b32_e32 v190, 16, v149
	v_and_b32_e32 v191, 0xffff0000, v149
	v_add_f32_dpp v212, v212, v212 row_half_mirror row_mask:0xf bank_mask:0xf bound_ctrl:1
	v_lshlrev_b32_e32 v192, 16, v150
	v_and_b32_e32 v193, 0xffff0000, v150
	v_lshlrev_b32_e32 v194, 16, v151
	v_and_b32_e32 v195, 0xffff0000, v151
	v_add_f32_dpp v212, v212, v212 row_mirror row_mask:0xf bank_mask:0xf bound_ctrl:1
	s_nop 0
	v_readlane_b32 s20, v212, 0
	v_readlane_b32 s21, v212, 16
	v_readlane_b32 s22, v212, 32
	v_readlane_b32 s49, v212, 48
	s_nop 1
	v_mov_b32_e32 v212, s21
	v_add_f32_e32 v212, s20, v212
	v_add_f32_e32 v212, s22, v212
	v_add_f32_e32 v212, s49, v212
	v_fmamk_f32 v212, v212, 0x3a800000, v214
	v_rsq_f32_e32 v212, v212
	s_nop 0
	v_pk_mul_f32 v[196:197], v[212:213], v[196:197] op_sel_hi:[0,1]
	v_pk_mul_f32 v[198:199], v[212:213], v[198:199] op_sel_hi:[0,1]
	v_pk_mul_f32 v[200:201], v[212:213], v[200:201] op_sel_hi:[0,1]
	v_pk_mul_f32 v[202:203], v[212:213], v[202:203] op_sel_hi:[0,1]
	v_pk_mul_f32 v[204:205], v[212:213], v[204:205] op_sel_hi:[0,1]
	v_pk_mul_f32 v[206:207], v[212:213], v[206:207] op_sel_hi:[0,1]
	v_pk_mul_f32 v[208:209], v[212:213], v[208:209] op_sel_hi:[0,1]
; __device__ __forceinline__ unsigned cvt_pk_bf16(float lo, float hi) { const f32x2_t v = {lo, hi}; const bf16x2_t b = __builtin_convertvector(v, bf16x2_t); return __builtin_bit_cast(unsigned, b); }
; __device__ __forceinline__ void rows_proc(PR P, const int mode, const int row, const int lane, float4 (&xv)[4], const float4 (&fo)[4], const float4 (&gp)[4], const float4 (&gn)[4]) {
;     ...
;     if (mode != 0) {
;         float ss = 0.f;
; #pragma unroll
;         for (int q = 0; q < 4; ++q) ss += fo[q].x * fo[q].x + fo[q].y * fo[q].y + fo[q].z * fo[q].z + fo[q].w * fo[q].w;
;         ss = wave_sum(ss); const float r = rsqrtf(ss * (1.0f / 1024.0f) + 1e-6f) * (mode == 2 ? 1.0f : 0.5f);
; #pragma unroll
;         for (int q = 0; q < 4; ++q) {
;             xv[q].x += fo[q].x * r * gp[q].x; xv[q].y += fo[q].y * r * gp[q].y; xv[q].z += fo[q].z * r * gp[q].z; xv[q].w += fo[q].w * r * gp[q].w;
;             if (mode == 3) { const f32x4 t_ = {xv[q].x, xv[q].y, xv[q].z, xv[q].w}; __builtin_nontemporal_store(t_, (f32x4*)(P.out + (size_t)row * 1024 + (q * 64 + lane) * 4)); }
;             else { bf16_t* xo = (mode == 1 ? (bf16_t*)P.out : (bf16_t*)(P.ws + WS_FO + 34603008)) + (size_t)row * 1024; u32x2 t; t.x = pg8::cvt_pk_bf16(xv[q].x, xv[q].y); t.y = pg8::cvt_pk_bf16(xv[q].z, xv[q].w);
;                 __builtin_nontemporal_store(t, (u32x2*)(xo + (q * 64 + lane) * 4)); } }
;         if (mode == 3) return;
;     }
;     float ss2 = 0.f;
; #pragma unroll
;     for (int q = 0; q < 4; ++q) ss2 += xv[q].x * xv[q].x + xv[q].y * xv[q].y + xv[q].z * xv[q].z + xv[q].w * xv[q].w;
;     ss2 = wave_sum(ss2); const float r2 = rsqrtf(ss2 * (1.0f / 1024.0f) + 1e-6f);
;     float* sh = nullptr;
;     if (mode == 1) { if (row < MP) { if ((row & 2047) == 2047) sh = P.out + O_SHP + (size_t)(row >> 11) * 1024; } else { const int s = row - MP; if ((s & 3) == 3) sh = P.out + O_SHS + (size_t)(s >> 2) * 1024; } }
; #pragma unroll
;     for (int q = 0; q < 4; ++q) {
;         float4 hv; hv.x = xv[q].x * r2 * gn[q].x; hv.y = xv[q].y * r2 * gn[q].y; hv.z = xv[q].z * r2 * gn[q].z; hv.w = xv[q].w * r2 * gn[q].w;
;         u32x2 w; w.x = pg8::cvt_pk_bf16(hv.x, hv.y); w.y = pg8::cvt_pk_bf16(hv.z, hv.w);
;         *(u32x2*)(XN + (size_t)row * 1024 + (q * 64 + lane) * 4) = w;
;         if (sh) *(float4*)(sh + (q * 64 + lane) * 4) = hv; }
	v_pk_mul_f32 v[210:211], v[212:213], v[210:211] op_sel_hi:[0,1]
	v_pk_fma_f32 v[180:181], v[0:1], v[196:197], v[180:181]
	v_pk_fma_f32 v[182:183], v[2:3], v[198:199], v[182:183]
	v_pk_fma_f32 v[184:185], v[4:5], v[200:201], v[184:185]
	v_pk_fma_f32 v[186:187], v[6:7], v[202:203], v[186:187]
	v_pk_fma_f32 v[188:189], v[8:9], v[204:205], v[188:189]
	v_pk_fma_f32 v[190:191], v[10:11], v[206:207], v[190:191]
	v_pk_fma_f32 v[192:193], v[12:13], v[208:209], v[192:193]
	v_pk_fma_f32 v[194:195], v[14:15], v[210:211], v[194:195]
	v_pk_mul_f32 v[212:213], v[180:181], v[180:181]
	v_pk_fma_f32 v[212:213], v[182:183], v[182:183], v[212:213]
	v_pk_fma_f32 v[212:213], v[184:185], v[184:185], v[212:213]
	v_pk_fma_f32 v[212:213], v[186:187], v[186:187], v[212:213]
	v_pk_fma_f32 v[212:213], v[188:189], v[188:189], v[212:213]
	v_pk_fma_f32 v[212:213], v[190:191], v[190:191], v[212:213]
	v_pk_fma_f32 v[212:213], v[192:193], v[192:193], v[212:213]
	v_pk_fma_f32 v[212:213], v[194:195], v[194:195], v[212:213]
	v_add_f32_e32 v212, v212, v213
	v_add_u32_e32 v35, 0x1000000, v36
	v_cvt_pk_bf16_f32 v216, v180, v181
	v_cvt_pk_bf16_f32 v217, v182, v183
	v_cvt_pk_bf16_f32 v218, v184, v185
	v_add_f32_dpp v212, v212, v212 quad_perm:[1,0,3,2] row_mask:0xf bank_mask:0xf bound_ctrl:1
	v_cvt_pk_bf16_f32 v219, v186, v187
	v_cvt_pk_bf16_f32 v220, v188, v189
	global_store_dwordx2 v35, v[216:217], s[14:15] offset:0 nt
	v_add_f32_dpp v212, v212, v212 quad_perm:[2,3,0,1] row_mask:0xf bank_mask:0xf bound_ctrl:1
	v_cvt_pk_bf16_f32 v221, v190, v191
	v_cvt_pk_bf16_f32 v222, v192, v193
	global_store_dwordx2 v35, v[218:219], s[14:15] offset:512 nt
	v_add_f32_dpp v212, v212, v212 row_half_mirror row_mask:0xf bank_mask:0xf bound_ctrl:1
	v_cvt_pk_bf16_f32 v223, v194, v195
	global_store_dwordx2 v35, v[220:221], s[14:15] offset:1024 nt
	global_store_dwordx2 v35, v[222:223], s[14:15] offset:1536 nt
	v_add_f32_dpp v212, v212, v212 row_mirror row_mask:0xf bank_mask:0xf bound_ctrl:1
	s_nop 0
	v_readlane_b32 s20, v212, 0
	v_readlane_b32 s21, v212, 16
	v_readlane_b32 s22, v212, 32
	v_readlane_b32 s49, v212, 48
	s_nop 1
	v_mov_b32_e32 v212, s21
	v_add_f32_e32 v212, s20, v212
	v_add_f32_e32 v212, s22, v212
	v_add_f32_e32 v212, s49, v212
	v_fmamk_f32 v212, v212, 0x3a800000, v214
	v_rsq_f32_e32 v212, v212
	s_nop 0
	v_pk_mul_f32 v[180:181], v[212:213], v[180:181] op_sel_hi:[0,1]
	v_pk_mul_f32 v[182:183], v[212:213], v[182:183] op_sel_hi:[0,1]
	v_pk_mul_f32 v[184:185], v[212:213], v[184:185] op_sel_hi:[0,1]
	v_pk_mul_f32 v[186:187], v[212:213], v[186:187] op_sel_hi:[0,1]
	v_pk_mul_f32 v[188:189], v[212:213], v[188:189] op_sel_hi:[0,1]
	v_pk_mul_f32 v[190:191], v[212:213], v[190:191] op_sel_hi:[0,1]
	v_pk_mul_f32 v[192:193], v[212:213], v[192:193] op_sel_hi:[0,1]
	v_pk_mul_f32 v[194:195], v[212:213], v[194:195] op_sel_hi:[0,1]
	v_pk_mul_f32 v[180:181], v[180:181], v[16:17]
	v_pk_mul_f32 v[182:183], v[182:183], v[18:19]
	v_pk_mul_f32 v[184:185], v[184:185], v[20:21]
	v_pk_mul_f32 v[186:187], v[186:187], v[22:23]
	v_pk_mul_f32 v[188:189], v[188:189], v[24:25]
	v_pk_mul_f32 v[190:191], v[190:191], v[26:27]
	v_pk_mul_f32 v[192:193], v[192:193], v[28:29]
	v_pk_mul_f32 v[194:195], v[194:195], v[30:31]
	v_cvt_pk_bf16_f32 v216, v180, v181
	v_cvt_pk_bf16_f32 v217, v182, v183
	v_cvt_pk_bf16_f32 v218, v184, v185
	v_cvt_pk_bf16_f32 v219, v186, v187
	v_cvt_pk_bf16_f32 v220, v188, v189
	v_cvt_pk_bf16_f32 v221, v190, v191
	v_cvt_pk_bf16_f32 v222, v192, v193
	v_cvt_pk_bf16_f32 v223, v194, v195
	global_store_dwordx2 v35, v[216:217], s[18:19] offset:0
	global_store_dwordx2 v35, v[218:219], s[18:19] offset:512
	global_store_dwordx2 v35, v[220:221], s[18:19] offset:1024
	global_store_dwordx2 v35, v[222:223], s[18:19] offset:1536
	s_waitcnt vmcnt(48)
	v_lshlrev_b32_e32 v196, 16, v88
	v_and_b32_e32 v197, 0xffff0000, v88
	v_lshlrev_b32_e32 v198, 16, v89
	v_and_b32_e32 v199, 0xffff0000, v89
	v_lshlrev_b32_e32 v200, 16, v90
	v_and_b32_e32 v201, 0xffff0000, v90
	v_lshlrev_b32_e32 v202, 16, v91
	v_and_b32_e32 v203, 0xffff0000, v91
	v_lshlrev_b32_e32 v204, 16, v92
	v_and_b32_e32 v205, 0xffff0000, v92
	v_lshlrev_b32_e32 v206, 16, v93
	v_and_b32_e32 v207, 0xffff0000, v93
	v_lshlrev_b32_e32 v208, 16, v94
	v_and_b32_e32 v209, 0xffff0000, v94
	v_lshlrev_b32_e32 v210, 16, v95
	v_and_b32_e32 v211, 0xffff0000, v95
	v_pk_mul_f32 v[212:213], v[196:197], v[196:197]
	v_pk_fma_f32 v[212:213], v[198:199], v[198:199], v[212:213]
	v_pk_fma_f32 v[212:213], v[200:201], v[200:201], v[212:213]
	v_pk_fma_f32 v[212:213], v[202:203], v[202:203], v[212:213]
	v_pk_fma_f32 v[212:213], v[204:205], v[204:205], v[212:213]
	v_pk_fma_f32 v[212:213], v[206:207], v[206:207], v[212:213]
	v_pk_fma_f32 v[212:213], v[208:209], v[208:209], v[212:213]
	v_pk_fma_f32 v[212:213], v[210:211], v[210:211], v[212:213]
	v_add_f32_e32 v212, v212, v213
	v_lshlrev_b32_e32 v180, 16, v80
	v_and_b32_e32 v181, 0xffff0000, v80
	v_lshlrev_b32_e32 v182, 16, v81
	v_and_b32_e32 v183, 0xffff0000, v81
	v_add_f32_dpp v212, v212, v212 quad_perm:[1,0,3,2] row_mask:0xf bank_mask:0xf bound_ctrl:1
	v_lshlrev_b32_e32 v184, 16, v82
	v_and_b32_e32 v185, 0xffff0000, v82
	v_lshlrev_b32_e32 v186, 16, v83
	v_and_b32_e32 v187, 0xffff0000, v83
	v_add_f32_dpp v212, v212, v212 quad_perm:[2,3,0,1] row_mask:0xf bank_mask:0xf bound_ctrl:1
	v_lshlrev_b32_e32 v188, 16, v84
	v_and_b32_e32 v189, 0xffff0000, v84
	v_lshlrev_b32_e32 v190, 16, v85
	v_and_b32_e32 v191, 0xffff0000, v85
	v_add_f32_dpp v212, v212, v212 row_half_mirror row_mask:0xf bank_mask:0xf bound_ctrl:1
	v_lshlrev_b32_e32 v192, 16, v86
	v_and_b32_e32 v193, 0xffff0000, v86
	v_lshlrev_b32_e32 v194, 16, v87
	v_and_b32_e32 v195, 0xffff0000, v87
; __device__ __forceinline__ unsigned cvt_pk_bf16(float lo, float hi) { const f32x2_t v = {lo, hi}; const bf16x2_t b = __builtin_convertvector(v, bf16x2_t); return __builtin_bit_cast(unsigned, b); }
; __device__ __forceinline__ void rows_proc(PR P, const int mode, const int row, const int lane, float4 (&xv)[4], const float4 (&fo)[4], const float4 (&gp)[4], const float4 (&gn)[4]) {
;     ...
;     if (mode != 0) {
;         float ss = 0.f;
; #pragma unroll
;         for (int q = 0; q < 4; ++q) ss += fo[q].x * fo[q].x + fo[q].y * fo[q].y + fo[q].z * fo[q].z + fo[q].w * fo[q].w;
;         ss = wave_sum(ss); const float r = rsqrtf(ss * (1.0f / 1024.0f) + 1e-6f) * (mode == 2 ? 1.0f : 0.5f);
; #pragma unroll
;         for (int q = 0; q < 4; ++q) {
;             xv[q].x += fo[q].x * r * gp[q].x; xv[q].y += fo[q].y * r * gp[q].y; xv[q].z += fo[q].z * r * gp[q].z; xv[q].w += fo[q].w * r * gp[q].w;
;             if (mode == 3) { const f32x4 t_ = {xv[q].x, xv[q].y, xv[q].z, xv[q].w}; __builtin_nontemporal_store(t_, (f32x4*)(P.out + (size_t)row * 1024 + (q * 64 + lane) * 4)); }
;             else { bf16_t* xo = (mode == 1 ? (bf16_t*)P.out : (bf16_t*)(P.ws + WS_FO + 34603008)) + (size_t)row * 1024; u32x2 t; t.x = pg8::cvt_pk_bf16(xv[q].x, xv[q].y); t.y = pg8::cvt_pk_bf16(xv[q].z, xv[q].w);
;                 __builtin_nontemporal_store(t, (u32x2*)(xo + (q * 64 + lane) * 4)); } }
;         if (mode == 3) return;
;     }
;     float ss2 = 0.f;
; #pragma unroll
;     for (int q = 0; q < 4; ++q) ss2 += xv[q].x * xv[q].x + xv[q].y * xv[q].y + xv[q].z * xv[q].z + xv[q].w * xv[q].w;
;     ss2 = wave_sum(ss2); const float r2 = rsqrtf(ss2 * (1.0f / 1024.0f) + 1e-6f);
;     float* sh = nullptr;
;     if (mode == 1) { if (row < MP) { if ((row & 2047) == 2047) sh = P.out + O_SHP + (size_t)(row >> 11) * 1024; } else { const int s = row - MP; if ((s & 3) == 3) sh = P.out + O_SHS + (size_t)(s >> 2) * 1024; } }
; #pragma unroll
;     for (int q = 0; q < 4; ++q) {
;         float4 hv; hv.x = xv[q].x * r2 * gn[q].x; hv.y = xv[q].y * r2 * gn[q].y; hv.z = xv[q].z * r2 * gn[q].z; hv.w = xv[q].w * r2 * gn[q].w;
;         u32x2 w; w.x = pg8::cvt_pk_bf16(hv.x, hv.y); w.y = pg8::cvt_pk_bf16(hv.z, hv.w);
;         *(u32x2*)(XN + (size_t)row * 1024 + (q * 64 + lane) * 4) = w;
;         if (sh) *(float4*)(sh + (q * 64 + lane) * 4) = hv; }
	v_add_f32_dpp v212, v212, v212 row_mirror row_mask:0xf bank_mask:0xf bound_ctrl:1
	s_nop 0
	v_readlane_b32 s20, v212, 0
	v_readlane_b32 s21, v212, 16
	v_readlane_b32 s22, v212, 32
	v_readlane_b32 s49, v212, 48
	s_nop 1
	v_mov_b32_e32 v212, s21
	v_add_f32_e32 v212, s20, v212
	v_add_f32_e32 v212, s22, v212
	v_add_f32_e32 v212, s49, v212
	v_fmamk_f32 v212, v212, 0x3a800000, v214
	v_rsq_f32_e32 v212, v212
	s_nop 0
	v_pk_mul_f32 v[196:197], v[212:213], v[196:197] op_sel_hi:[0,1]
	v_pk_mul_f32 v[198:199], v[212:213], v[198:199] op_sel_hi:[0,1]
	v_pk_mul_f32 v[200:201], v[212:213], v[200:201] op_sel_hi:[0,1]
	v_pk_mul_f32 v[202:203], v[212:213], v[202:203] op_sel_hi:[0,1]
	v_pk_mul_f32 v[204:205], v[212:213], v[204:205] op_sel_hi:[0,1]
	v_pk_mul_f32 v[206:207], v[212:213], v[206:207] op_sel_hi:[0,1]
	v_pk_mul_f32 v[208:209], v[212:213], v[208:209] op_sel_hi:[0,1]
	v_pk_mul_f32 v[210:211], v[212:213], v[210:211] op_sel_hi:[0,1]
	v_pk_fma_f32 v[180:181], v[0:1], v[196:197], v[180:181]
	v_pk_fma_f32 v[182:183], v[2:3], v[198:199], v[182:183]
	v_pk_fma_f32 v[184:185], v[4:5], v[200:201], v[184:185]
	v_pk_fma_f32 v[186:187], v[6:7], v[202:203], v[186:187]
	v_pk_fma_f32 v[188:189], v[8:9], v[204:205], v[188:189]
	v_pk_fma_f32 v[190:191], v[10:11], v[206:207], v[190:191]
	v_pk_fma_f32 v[192:193], v[12:13], v[208:209], v[192:193]
	v_pk_fma_f32 v[194:195], v[14:15], v[210:211], v[194:195]
	v_pk_mul_f32 v[212:213], v[180:181], v[180:181]
	v_pk_fma_f32 v[212:213], v[182:183], v[182:183], v[212:213]
	v_pk_fma_f32 v[212:213], v[184:185], v[184:185], v[212:213]
	v_pk_fma_f32 v[212:213], v[186:187], v[186:187], v[212:213]
	v_pk_fma_f32 v[212:213], v[188:189], v[188:189], v[212:213]
	v_pk_fma_f32 v[212:213], v[190:191], v[190:191], v[212:213]
	v_pk_fma_f32 v[212:213], v[192:193], v[192:193], v[212:213]
	v_pk_fma_f32 v[212:213], v[194:195], v[194:195], v[212:213]
	v_add_f32_e32 v212, v212, v213
	v_add_u32_e32 v35, 0x1400000, v36
	v_cvt_pk_bf16_f32 v216, v180, v181
	v_cvt_pk_bf16_f32 v217, v182, v183
	v_cvt_pk_bf16_f32 v218, v184, v185
	v_add_f32_dpp v212, v212, v212 quad_perm:[1,0,3,2] row_mask:0xf bank_mask:0xf bound_ctrl:1
	v_cvt_pk_bf16_f32 v219, v186, v187
	v_cvt_pk_bf16_f32 v220, v188, v189
	global_store_dwordx2 v35, v[216:217], s[14:15] offset:0 nt
	v_add_f32_dpp v212, v212, v212 quad_perm:[2,3,0,1] row_mask:0xf bank_mask:0xf bound_ctrl:1
	v_cvt_pk_bf16_f32 v221, v190, v191
	v_cvt_pk_bf16_f32 v222, v192, v193
	global_store_dwordx2 v35, v[218:219], s[14:15] offset:512 nt
	v_add_f32_dpp v212, v212, v212 row_half_mirror row_mask:0xf bank_mask:0xf bound_ctrl:1
	v_cvt_pk_bf16_f32 v223, v194, v195
	global_store_dwordx2 v35, v[220:221], s[14:15] offset:1024 nt
	global_store_dwordx2 v35, v[222:223], s[14:15] offset:1536 nt
	v_add_f32_dpp v212, v212, v212 row_mirror row_mask:0xf bank_mask:0xf bound_ctrl:1
	s_nop 0
	v_readlane_b32 s20, v212, 0
	v_readlane_b32 s21, v212, 16
	v_readlane_b32 s22, v212, 32
	v_readlane_b32 s49, v212, 48
	s_nop 1
	v_mov_b32_e32 v212, s21
	v_add_f32_e32 v212, s20, v212
	v_add_f32_e32 v212, s22, v212
	v_add_f32_e32 v212, s49, v212
	v_fmamk_f32 v212, v212, 0x3a800000, v214
	v_rsq_f32_e32 v212, v212
	s_nop 0
	v_pk_mul_f32 v[180:181], v[212:213], v[180:181] op_sel_hi:[0,1]
	v_pk_mul_f32 v[182:183], v[212:213], v[182:183] op_sel_hi:[0,1]
	v_pk_mul_f32 v[184:185], v[212:213], v[184:185] op_sel_hi:[0,1]
	v_pk_mul_f32 v[186:187], v[212:213], v[186:187] op_sel_hi:[0,1]
	v_pk_mul_f32 v[188:189], v[212:213], v[188:189] op_sel_hi:[0,1]
	v_pk_mul_f32 v[190:191], v[212:213], v[190:191] op_sel_hi:[0,1]
	v_pk_mul_f32 v[192:193], v[212:213], v[192:193] op_sel_hi:[0,1]
	v_pk_mul_f32 v[194:195], v[212:213], v[194:195] op_sel_hi:[0,1]
	v_pk_mul_f32 v[180:181], v[180:181], v[16:17]
	v_pk_mul_f32 v[182:183], v[182:183], v[18:19]
	v_pk_mul_f32 v[184:185], v[184:185], v[20:21]
	v_pk_mul_f32 v[186:187], v[186:187], v[22:23]
	v_pk_mul_f32 v[188:189], v[188:189], v[24:25]
	v_pk_mul_f32 v[190:191], v[190:191], v[26:27]
	v_pk_mul_f32 v[192:193], v[192:193], v[28:29]
	v_pk_mul_f32 v[194:195], v[194:195], v[30:31]
	v_cvt_pk_bf16_f32 v216, v180, v181
	v_cvt_pk_bf16_f32 v217, v182, v183
	v_cvt_pk_bf16_f32 v218, v184, v185
	v_cvt_pk_bf16_f32 v219, v186, v187
	v_cvt_pk_bf16_f32 v220, v188, v189
	v_cvt_pk_bf16_f32 v221, v190, v191
	v_cvt_pk_bf16_f32 v222, v192, v193
	v_cvt_pk_bf16_f32 v223, v194, v195
	global_store_dwordx2 v35, v[216:217], s[18:19] offset:0
	global_store_dwordx2 v35, v[218:219], s[18:19] offset:512
	global_store_dwordx2 v35, v[220:221], s[18:19] offset:1024
	global_store_dwordx2 v35, v[222:223], s[18:19] offset:1536
	s_waitcnt vmcnt(40)
; __device__ __forceinline__ unsigned cvt_pk_bf16(float lo, float hi) { const f32x2_t v = {lo, hi}; const bf16x2_t b = __builtin_convertvector(v, bf16x2_t); return __builtin_bit_cast(unsigned, b); }
; __device__ __forceinline__ void rows_proc(PR P, const int mode, const int row, const int lane, float4 (&xv)[4], const float4 (&fo)[4], const float4 (&gp)[4], const float4 (&gn)[4]) {
;     ...
;     if (mode != 0) {
;         float ss = 0.f;
; #pragma unroll
;         for (int q = 0; q < 4; ++q) ss += fo[q].x * fo[q].x + fo[q].y * fo[q].y + fo[q].z * fo[q].z + fo[q].w * fo[q].w;
;         ss = wave_sum(ss); const float r = rsqrtf(ss * (1.0f / 1024.0f) + 1e-6f) * (mode == 2 ? 1.0f : 0.5f);
; #pragma unroll
;         for (int q = 0; q < 4; ++q) {
;             xv[q].x += fo[q].x * r * gp[q].x; xv[q].y += fo[q].y * r * gp[q].y; xv[q].z += fo[q].z * r * gp[q].z; xv[q].w += fo[q].w * r * gp[q].w;
;             if (mode == 3) { const f32x4 t_ = {xv[q].x, xv[q].y, xv[q].z, xv[q].w}; __builtin_nontemporal_store(t_, (f32x4*)(P.out + (size_t)row * 1024 + (q * 64 + lane) * 4)); }
;             else { bf16_t* xo = (mode == 1 ? (bf16_t*)P.out : (bf16_t*)(P.ws + WS_FO + 34603008)) + (size_t)row * 1024; u32x2 t; t.x = pg8::cvt_pk_bf16(xv[q].x, xv[q].y); t.y = pg8::cvt_pk_bf16(xv[q].z, xv[q].w);
;                 __builtin_nontemporal_store(t, (u32x2*)(xo + (q * 64 + lane) * 4)); } }
;         if (mode == 3) return;
;     }
;     float ss2 = 0.f;
; #pragma unroll
;     for (int q = 0; q < 4; ++q) ss2 += xv[q].x * xv[q].x + xv[q].y * xv[q].y + xv[q].z * xv[q].z + xv[q].w * xv[q].w;
;     ss2 = wave_sum(ss2); const float r2 = rsqrtf(ss2 * (1.0f / 1024.0f) + 1e-6f);
;     float* sh = nullptr;
;     if (mode == 1) { if (row < MP) { if ((row & 2047) == 2047) sh = P.out + O_SHP + (size_t)(row >> 11) * 1024; } else { const int s = row - MP; if ((s & 3) == 3) sh = P.out + O_SHS + (size_t)(s >> 2) * 1024; } }
; #pragma unroll
;     for (int q = 0; q < 4; ++q) {
;         float4 hv; hv.x = xv[q].x * r2 * gn[q].x; hv.y = xv[q].y * r2 * gn[q].y; hv.z = xv[q].z * r2 * gn[q].z; hv.w = xv[q].w * r2 * gn[q].w;
;         u32x2 w; w.x = pg8::cvt_pk_bf16(hv.x, hv.y); w.y = pg8::cvt_pk_bf16(hv.z, hv.w);
;         *(u32x2*)(XN + (size_t)row * 1024 + (q * 64 + lane) * 4) = w;
;         if (sh) *(float4*)(sh + (q * 64 + lane) * 4) = hv; }
	v_lshlrev_b32_e32 v196, 16, v104
	v_and_b32_e32 v197, 0xffff0000, v104
	v_lshlrev_b32_e32 v198, 16, v105
	v_and_b32_e32 v199, 0xffff0000, v105
	v_lshlrev_b32_e32 v200, 16, v106
	v_and_b32_e32 v201, 0xffff0000, v106
	v_lshlrev_b32_e32 v202, 16, v107
	v_and_b32_e32 v203, 0xffff0000, v107
	v_lshlrev_b32_e32 v204, 16, v108
	v_and_b32_e32 v205, 0xffff0000, v108
	v_lshlrev_b32_e32 v206, 16, v109
	v_and_b32_e32 v207, 0xffff0000, v109
	v_lshlrev_b32_e32 v208, 16, v110
	v_and_b32_e32 v209, 0xffff0000, v110
	v_lshlrev_b32_e32 v210, 16, v111
	v_and_b32_e32 v211, 0xffff0000, v111
	v_pk_mul_f32 v[212:213], v[196:197], v[196:197]
	v_pk_fma_f32 v[212:213], v[198:199], v[198:199], v[212:213]
	v_pk_fma_f32 v[212:213], v[200:201], v[200:201], v[212:213]
	v_pk_fma_f32 v[212:213], v[202:203], v[202:203], v[212:213]
	v_pk_fma_f32 v[212:213], v[204:205], v[204:205], v[212:213]
	v_pk_fma_f32 v[212:213], v[206:207], v[206:207], v[212:213]
	v_pk_fma_f32 v[212:213], v[208:209], v[208:209], v[212:213]
	v_pk_fma_f32 v[212:213], v[210:211], v[210:211], v[212:213]
	v_add_f32_e32 v212, v212, v213
	v_lshlrev_b32_e32 v180, 16, v96
	v_and_b32_e32 v181, 0xffff0000, v96
	v_lshlrev_b32_e32 v182, 16, v97
	v_and_b32_e32 v183, 0xffff0000, v97
	v_add_f32_dpp v212, v212, v212 quad_perm:[1,0,3,2] row_mask:0xf bank_mask:0xf bound_ctrl:1
	v_lshlrev_b32_e32 v184, 16, v98
	v_and_b32_e32 v185, 0xffff0000, v98
	v_lshlrev_b32_e32 v186, 16, v99
	v_and_b32_e32 v187, 0xffff0000, v99
	v_add_f32_dpp v212, v212, v212 quad_perm:[2,3,0,1] row_mask:0xf bank_mask:0xf bound_ctrl:1
	v_lshlrev_b32_e32 v188, 16, v100
	v_and_b32_e32 v189, 0xffff0000, v100
	v_lshlrev_b32_e32 v190, 16, v101
	v_and_b32_e32 v191, 0xffff0000, v101
	v_add_f32_dpp v212, v212, v212 row_half_mirror row_mask:0xf bank_mask:0xf bound_ctrl:1
	v_lshlrev_b32_e32 v192, 16, v102
	v_and_b32_e32 v193, 0xffff0000, v102
	v_lshlrev_b32_e32 v194, 16, v103
	v_and_b32_e32 v195, 0xffff0000, v103
	v_add_f32_dpp v212, v212, v212 row_mirror row_mask:0xf bank_mask:0xf bound_ctrl:1
	s_nop 0
	v_readlane_b32 s20, v212, 0
	v_readlane_b32 s21, v212, 16
	v_readlane_b32 s22, v212, 32
	v_readlane_b32 s49, v212, 48
	s_nop 1
	v_mov_b32_e32 v212, s21
	v_add_f32_e32 v212, s20, v212
	v_add_f32_e32 v212, s22, v212
	v_add_f32_e32 v212, s49, v212
	v_fmamk_f32 v212, v212, 0x3a800000, v214
	v_rsq_f32_e32 v212, v212
	s_nop 0
	v_pk_mul_f32 v[196:197], v[212:213], v[196:197] op_sel_hi:[0,1]
	v_pk_mul_f32 v[198:199], v[212:213], v[198:199] op_sel_hi:[0,1]
	v_pk_mul_f32 v[200:201], v[212:213], v[200:201] op_sel_hi:[0,1]
	v_pk_mul_f32 v[202:203], v[212:213], v[202:203] op_sel_hi:[0,1]
	v_pk_mul_f32 v[204:205], v[212:213], v[204:205] op_sel_hi:[0,1]
	v_pk_mul_f32 v[206:207], v[212:213], v[206:207] op_sel_hi:[0,1]
	v_pk_mul_f32 v[208:209], v[212:213], v[208:209] op_sel_hi:[0,1]
	v_pk_mul_f32 v[210:211], v[212:213], v[210:211] op_sel_hi:[0,1]
	v_pk_fma_f32 v[180:181], v[0:1], v[196:197], v[180:181]
	v_pk_fma_f32 v[182:183], v[2:3], v[198:199], v[182:183]
	v_pk_fma_f32 v[184:185], v[4:5], v[200:201], v[184:185]
	v_pk_fma_f32 v[186:187], v[6:7], v[202:203], v[186:187]
	v_pk_fma_f32 v[188:189], v[8:9], v[204:205], v[188:189]
	v_pk_fma_f32 v[190:191], v[10:11], v[206:207], v[190:191]
	v_pk_fma_f32 v[192:193], v[12:13], v[208:209], v[192:193]
	v_pk_fma_f32 v[194:195], v[14:15], v[210:211], v[194:195]
	v_pk_mul_f32 v[212:213], v[180:181], v[180:181]
	v_pk_fma_f32 v[212:213], v[182:183], v[182:183], v[212:213]
	v_pk_fma_f32 v[212:213], v[184:185], v[184:185], v[212:213]
	v_pk_fma_f32 v[212:213], v[186:187], v[186:187], v[212:213]
	v_pk_fma_f32 v[212:213], v[188:189], v[188:189], v[212:213]
	v_pk_fma_f32 v[212:213], v[190:191], v[190:191], v[212:213]
	v_pk_fma_f32 v[212:213], v[192:193], v[192:193], v[212:213]
	v_pk_fma_f32 v[212:213], v[194:195], v[194:195], v[212:213]
	v_add_f32_e32 v212, v212, v213
	v_add_u32_e32 v35, 0x1800000, v36
	v_cvt_pk_bf16_f32 v216, v180, v181
	v_cvt_pk_bf16_f32 v217, v182, v183
	v_cvt_pk_bf16_f32 v218, v184, v185
	v_add_f32_dpp v212, v212, v212 quad_perm:[1,0,3,2] row_mask:0xf bank_mask:0xf bound_ctrl:1
	v_cvt_pk_bf16_f32 v219, v186, v187
	v_cvt_pk_bf16_f32 v220, v188, v189
	global_store_dwordx2 v35, v[216:217], s[14:15] offset:0 nt
	v_add_f32_dpp v212, v212, v212 quad_perm:[2,3,0,1] row_mask:0xf bank_mask:0xf bound_ctrl:1
	v_cvt_pk_bf16_f32 v221, v190, v191
	v_cvt_pk_bf16_f32 v222, v192, v193
	global_store_dwordx2 v35, v[218:219], s[14:15] offset:512 nt
	v_add_f32_dpp v212, v212, v212 row_half_mirror row_mask:0xf bank_mask:0xf bound_ctrl:1
	v_cvt_pk_bf16_f32 v223, v194, v195
	global_store_dwordx2 v35, v[220:221], s[14:15] offset:1024 nt
	global_store_dwordx2 v35, v[222:223], s[14:15] offset:1536 nt
	v_add_f32_dpp v212, v212, v212 row_mirror row_mask:0xf bank_mask:0xf bound_ctrl:1
	s_nop 0
	v_readlane_b32 s20, v212, 0
	v_readlane_b32 s21, v212, 16
	v_readlane_b32 s22, v212, 32
	v_readlane_b32 s49, v212, 48
	s_nop 1
	v_mov_b32_e32 v212, s21
	v_add_f32_e32 v212, s20, v212
	v_add_f32_e32 v212, s22, v212
	v_add_f32_e32 v212, s49, v212
	v_fmamk_f32 v212, v212, 0x3a800000, v214
	v_rsq_f32_e32 v212, v212
	s_nop 0
	v_pk_mul_f32 v[180:181], v[212:213], v[180:181] op_sel_hi:[0,1]
	v_pk_mul_f32 v[182:183], v[212:213], v[182:183] op_sel_hi:[0,1]
	v_pk_mul_f32 v[184:185], v[212:213], v[184:185] op_sel_hi:[0,1]
	v_pk_mul_f32 v[186:187], v[212:213], v[186:187] op_sel_hi:[0,1]
	v_pk_mul_f32 v[188:189], v[212:213], v[188:189] op_sel_hi:[0,1]
	v_pk_mul_f32 v[190:191], v[212:213], v[190:191] op_sel_hi:[0,1]
	v_pk_mul_f32 v[192:193], v[212:213], v[192:193] op_sel_hi:[0,1]
	v_pk_mul_f32 v[194:195], v[212:213], v[194:195] op_sel_hi:[0,1]
	v_pk_mul_f32 v[180:181], v[180:181], v[16:17]
	v_pk_mul_f32 v[182:183], v[182:183], v[18:19]
	v_pk_mul_f32 v[184:185], v[184:185], v[20:21]
	v_pk_mul_f32 v[186:187], v[186:187], v[22:23]
	v_pk_mul_f32 v[188:189], v[188:189], v[24:25]
	v_pk_mul_f32 v[190:191], v[190:191], v[26:27]
	v_pk_mul_f32 v[192:193], v[192:193], v[28:29]
	v_pk_mul_f32 v[194:195], v[194:195], v[30:31]
	v_cvt_pk_bf16_f32 v216, v180, v181
	v_cvt_pk_bf16_f32 v217, v182, v183
	v_cvt_pk_bf16_f32 v218, v184, v185
	v_cvt_pk_bf16_f32 v219, v186, v187
	v_cvt_pk_bf16_f32 v220, v188, v189
	v_cvt_pk_bf16_f32 v221, v190, v191
	v_cvt_pk_bf16_f32 v222, v192, v193
	v_cvt_pk_bf16_f32 v223, v194, v195
	global_store_dwordx2 v35, v[216:217], s[18:19] offset:0
	global_store_dwordx2 v35, v[218:219], s[18:19] offset:512
	global_store_dwordx2 v35, v[220:221], s[18:19] offset:1024
	global_store_dwordx2 v35, v[222:223], s[18:19] offset:1536
	s_waitcnt vmcnt(32)
; __device__ __forceinline__ unsigned cvt_pk_bf16(float lo, float hi) { const f32x2_t v = {lo, hi}; const bf16x2_t b = __builtin_convertvector(v, bf16x2_t); return __builtin_bit_cast(unsigned, b); }
; __device__ __forceinline__ void rows_proc(PR P, const int mode, const int row, const int lane, float4 (&xv)[4], const float4 (&fo)[4], const float4 (&gp)[4], const float4 (&gn)[4]) {
;     ...
;     if (mode != 0) {
;         float ss = 0.f;
; #pragma unroll
;         for (int q = 0; q < 4; ++q) ss += fo[q].x * fo[q].x + fo[q].y * fo[q].y + fo[q].z * fo[q].z + fo[q].w * fo[q].w;
;         ss = wave_sum(ss); const float r = rsqrtf(ss * (1.0f / 1024.0f) + 1e-6f) * (mode == 2 ? 1.0f : 0.5f);
; #pragma unroll
;         for (int q = 0; q < 4; ++q) {
;             xv[q].x += fo[q].x * r * gp[q].x; xv[q].y += fo[q].y * r * gp[q].y; xv[q].z += fo[q].z * r * gp[q].z; xv[q].w += fo[q].w * r * gp[q].w;
;             if (mode == 3) { const f32x4 t_ = {xv[q].x, xv[q].y, xv[q].z, xv[q].w}; __builtin_nontemporal_store(t_, (f32x4*)(P.out + (size_t)row * 1024 + (q * 64 + lane) * 4)); }
;             else { bf16_t* xo = (mode == 1 ? (bf16_t*)P.out : (bf16_t*)(P.ws + WS_FO + 34603008)) + (size_t)row * 1024; u32x2 t; t.x = pg8::cvt_pk_bf16(xv[q].x, xv[q].y); t.y = pg8::cvt_pk_bf16(xv[q].z, xv[q].w);
;                 __builtin_nontemporal_store(t, (u32x2*)(xo + (q * 64 + lane) * 4)); } }
;         if (mode == 3) return;
;     }
;     float ss2 = 0.f;
; #pragma unroll
;     for (int q = 0; q < 4; ++q) ss2 += xv[q].x * xv[q].x + xv[q].y * xv[q].y + xv[q].z * xv[q].z + xv[q].w * xv[q].w;
;     ss2 = wave_sum(ss2); const float r2 = rsqrtf(ss2 * (1.0f / 1024.0f) + 1e-6f);
;     float* sh = nullptr;
;     if (mode == 1) { if (row < MP) { if ((row & 2047) == 2047) sh = P.out + O_SHP + (size_t)(row >> 11) * 1024; } else { const int s = row - MP; if ((s & 3) == 3) sh = P.out + O_SHS + (size_t)(s >> 2) * 1024; } }
; #pragma unroll
;     for (int q = 0; q < 4; ++q) {
;         float4 hv; hv.x = xv[q].x * r2 * gn[q].x; hv.y = xv[q].y * r2 * gn[q].y; hv.z = xv[q].z * r2 * gn[q].z; hv.w = xv[q].w * r2 * gn[q].w;
;         u32x2 w; w.x = pg8::cvt_pk_bf16(hv.x, hv.y); w.y = pg8::cvt_pk_bf16(hv.z, hv.w);
;         *(u32x2*)(XN + (size_t)row * 1024 + (q * 64 + lane) * 4) = w;
;         if (sh) *(float4*)(sh + (q * 64 + lane) * 4) = hv; }
	v_lshlrev_b32_e32 v196, 16, v120
	v_and_b32_e32 v197, 0xffff0000, v120
	v_lshlrev_b32_e32 v198, 16, v121
	v_and_b32_e32 v199, 0xffff0000, v121
	v_lshlrev_b32_e32 v200, 16, v122
	v_and_b32_e32 v201, 0xffff0000, v122
	v_lshlrev_b32_e32 v202, 16, v123
	v_and_b32_e32 v203, 0xffff0000, v123
	v_lshlrev_b32_e32 v204, 16, v124
	v_and_b32_e32 v205, 0xffff0000, v124
	v_lshlrev_b32_e32 v206, 16, v125
	v_and_b32_e32 v207, 0xffff0000, v125
	v_lshlrev_b32_e32 v208, 16, v126
	v_and_b32_e32 v209, 0xffff0000, v126
	v_lshlrev_b32_e32 v210, 16, v127
	v_and_b32_e32 v211, 0xffff0000, v127
	v_pk_mul_f32 v[212:213], v[196:197], v[196:197]
	v_pk_fma_f32 v[212:213], v[198:199], v[198:199], v[212:213]
	v_pk_fma_f32 v[212:213], v[200:201], v[200:201], v[212:213]
	v_pk_fma_f32 v[212:213], v[202:203], v[202:203], v[212:213]
	v_pk_fma_f32 v[212:213], v[204:205], v[204:205], v[212:213]
	v_pk_fma_f32 v[212:213], v[206:207], v[206:207], v[212:213]
	v_pk_fma_f32 v[212:213], v[208:209], v[208:209], v[212:213]
	v_pk_fma_f32 v[212:213], v[210:211], v[210:211], v[212:213]
	v_add_f32_e32 v212, v212, v213
	v_lshlrev_b32_e32 v180, 16, v112
	v_and_b32_e32 v181, 0xffff0000, v112
	v_lshlrev_b32_e32 v182, 16, v113
	v_and_b32_e32 v183, 0xffff0000, v113
	v_add_f32_dpp v212, v212, v212 quad_perm:[1,0,3,2] row_mask:0xf bank_mask:0xf bound_ctrl:1
	v_lshlrev_b32_e32 v184, 16, v114
	v_and_b32_e32 v185, 0xffff0000, v114
	v_lshlrev_b32_e32 v186, 16, v115
	v_and_b32_e32 v187, 0xffff0000, v115
	v_add_f32_dpp v212, v212, v212 quad_perm:[2,3,0,1] row_mask:0xf bank_mask:0xf bound_ctrl:1
	v_lshlrev_b32_e32 v188, 16, v116
	v_and_b32_e32 v189, 0xffff0000, v116
	v_lshlrev_b32_e32 v190, 16, v117
	v_and_b32_e32 v191, 0xffff0000, v117
	v_add_f32_dpp v212, v212, v212 row_half_mirror row_mask:0xf bank_mask:0xf bound_ctrl:1
	v_lshlrev_b32_e32 v192, 16, v118
	v_and_b32_e32 v193, 0xffff0000, v118
	v_lshlrev_b32_e32 v194, 16, v119
	v_and_b32_e32 v195, 0xffff0000, v119
	v_add_f32_dpp v212, v212, v212 row_mirror row_mask:0xf bank_mask:0xf bound_ctrl:1
	s_nop 0
	v_readlane_b32 s20, v212, 0
	v_readlane_b32 s21, v212, 16
	v_readlane_b32 s22, v212, 32
	v_readlane_b32 s49, v212, 48
	s_nop 1
	v_mov_b32_e32 v212, s21
	v_add_f32_e32 v212, s20, v212
	v_add_f32_e32 v212, s22, v212
	v_add_f32_e32 v212, s49, v212
	v_fmamk_f32 v212, v212, 0x3a800000, v214
	v_rsq_f32_e32 v212, v212
	s_nop 0
	v_pk_mul_f32 v[196:197], v[212:213], v[196:197] op_sel_hi:[0,1]
	v_pk_mul_f32 v[198:199], v[212:213], v[198:199] op_sel_hi:[0,1]
	v_pk_mul_f32 v[200:201], v[212:213], v[200:201] op_sel_hi:[0,1]
	v_pk_mul_f32 v[202:203], v[212:213], v[202:203] op_sel_hi:[0,1]
	v_pk_mul_f32 v[204:205], v[212:213], v[204:205] op_sel_hi:[0,1]
	v_pk_mul_f32 v[206:207], v[212:213], v[206:207] op_sel_hi:[0,1]
	v_pk_mul_f32 v[208:209], v[212:213], v[208:209] op_sel_hi:[0,1]
	v_pk_mul_f32 v[210:211], v[212:213], v[210:211] op_sel_hi:[0,1]
	v_pk_fma_f32 v[180:181], v[0:1], v[196:197], v[180:181]
	v_pk_fma_f32 v[182:183], v[2:3], v[198:199], v[182:183]
	v_pk_fma_f32 v[184:185], v[4:5], v[200:201], v[184:185]
	v_pk_fma_f32 v[186:187], v[6:7], v[202:203], v[186:187]
	v_pk_fma_f32 v[188:189], v[8:9], v[204:205], v[188:189]
	v_pk_fma_f32 v[190:191], v[10:11], v[206:207], v[190:191]
	v_pk_fma_f32 v[192:193], v[12:13], v[208:209], v[192:193]
	v_pk_fma_f32 v[194:195], v[14:15], v[210:211], v[194:195]
	v_pk_mul_f32 v[212:213], v[180:181], v[180:181]
	v_pk_fma_f32 v[212:213], v[182:183], v[182:183], v[212:213]
	v_pk_fma_f32 v[212:213], v[184:185], v[184:185], v[212:213]
	v_pk_fma_f32 v[212:213], v[186:187], v[186:187], v[212:213]
	v_pk_fma_f32 v[212:213], v[188:189], v[188:189], v[212:213]
	v_pk_fma_f32 v[212:213], v[190:191], v[190:191], v[212:213]
	v_pk_fma_f32 v[212:213], v[192:193], v[192:193], v[212:213]
	v_pk_fma_f32 v[212:213], v[194:195], v[194:195], v[212:213]
	v_add_f32_e32 v212, v212, v213
	v_add_u32_e32 v35, 0x1c00000, v36
	v_cvt_pk_bf16_f32 v216, v180, v181
	v_cvt_pk_bf16_f32 v217, v182, v183
	v_cvt_pk_bf16_f32 v218, v184, v185
	v_add_f32_dpp v212, v212, v212 quad_perm:[1,0,3,2] row_mask:0xf bank_mask:0xf bound_ctrl:1
	v_cvt_pk_bf16_f32 v219, v186, v187
	v_cvt_pk_bf16_f32 v220, v188, v189
	global_store_dwordx2 v35, v[216:217], s[14:15] offset:0 nt
	v_add_f32_dpp v212, v212, v212 quad_perm:[2,3,0,1] row_mask:0xf bank_mask:0xf bound_ctrl:1
	v_cvt_pk_bf16_f32 v221, v190, v191
	v_cvt_pk_bf16_f32 v222, v192, v193
	global_store_dwordx2 v35, v[218:219], s[14:15] offset:512 nt
	v_add_f32_dpp v212, v212, v212 row_half_mirror row_mask:0xf bank_mask:0xf bound_ctrl:1
	v_cvt_pk_bf16_f32 v223, v194, v195
	global_store_dwordx2 v35, v[220:221], s[14:15] offset:1024 nt
	global_store_dwordx2 v35, v[222:223], s[14:15] offset:1536 nt
	v_add_f32_dpp v212, v212, v212 row_mirror row_mask:0xf bank_mask:0xf bound_ctrl:1
	s_nop 0
	v_readlane_b32 s20, v212, 0
	v_readlane_b32 s21, v212, 16
	v_readlane_b32 s22, v212, 32
	v_readlane_b32 s49, v212, 48
	s_nop 1
	v_mov_b32_e32 v212, s21
	v_add_f32_e32 v212, s20, v212
	v_add_f32_e32 v212, s22, v212
	v_add_f32_e32 v212, s49, v212
	v_fmamk_f32 v212, v212, 0x3a800000, v214
	v_rsq_f32_e32 v212, v212
	s_nop 0
	v_pk_mul_f32 v[180:181], v[212:213], v[180:181] op_sel_hi:[0,1]
	v_pk_mul_f32 v[182:183], v[212:213], v[182:183] op_sel_hi:[0,1]
	v_pk_mul_f32 v[184:185], v[212:213], v[184:185] op_sel_hi:[0,1]
	v_pk_mul_f32 v[186:187], v[212:213], v[186:187] op_sel_hi:[0,1]
	v_pk_mul_f32 v[188:189], v[212:213], v[188:189] op_sel_hi:[0,1]
	v_pk_mul_f32 v[190:191], v[212:213], v[190:191] op_sel_hi:[0,1]
	v_pk_mul_f32 v[192:193], v[212:213], v[192:193] op_sel_hi:[0,1]
	v_pk_mul_f32 v[194:195], v[212:213], v[194:195] op_sel_hi:[0,1]
	v_pk_mul_f32 v[180:181], v[180:181], v[16:17]
	v_pk_mul_f32 v[182:183], v[182:183], v[18:19]
	v_pk_mul_f32 v[184:185], v[184:185], v[20:21]
	v_pk_mul_f32 v[186:187], v[186:187], v[22:23]
	v_pk_mul_f32 v[188:189], v[188:189], v[24:25]
	v_pk_mul_f32 v[190:191], v[190:191], v[26:27]
	v_pk_mul_f32 v[192:193], v[192:193], v[28:29]
	v_pk_mul_f32 v[194:195], v[194:195], v[30:31]
	v_cvt_pk_bf16_f32 v216, v180, v181
	v_cvt_pk_bf16_f32 v217, v182, v183
	v_cvt_pk_bf16_f32 v218, v184, v185
	v_cvt_pk_bf16_f32 v219, v186, v187
	v_cvt_pk_bf16_f32 v220, v188, v189
	v_cvt_pk_bf16_f32 v221, v190, v191
	v_cvt_pk_bf16_f32 v222, v192, v193
	v_cvt_pk_bf16_f32 v223, v194, v195
	global_store_dwordx2 v35, v[216:217], s[18:19] offset:0
	global_store_dwordx2 v35, v[218:219], s[18:19] offset:512
	global_store_dwordx2 v35, v[220:221], s[18:19] offset:1024
	global_store_dwordx2 v35, v[222:223], s[18:19] offset:1536
	s_mov_b32 s49, 0
